# v7 plus hand-written kk/qk decay-mask epilogue in delta_prep (4 instances): LDS reads hoisted, branch-free, b128 Mm stores
# speedup vs baseline: 1.0045x; 1.0006x over previous
; __device__ __forceinline__ float delta_prep(const Params& p, int l, int h, bool isP, int grow0, int t0, int nvalid, int bb, char* sm) {
;     ...
;     bfraw* qh = (bfraw*)(sm + L_QG);
;     bfraw* kh = (bfraw*)(sm + L_W);
;     *(uint4*)(qh + rl * 136 + cg8 * 16) = pack8(qf); *(uint4*)(qh + rl * 136 + cg8 * 16 + 8) = pack8(qf + 8);
;     *(uint4*)(kh + rl * 136 + cg8 * 16) = pack8(kf); *(uint4*)(kh + rl * 136 + cg8 * 16 + 8) = pack8(kf + 8);
;   }
;   __syncthreads();
;   {
;     float* rhs = (float*)(sm + L_RHS);
;     const float bt = misc[64 + rl], eg = misc[128 + rl];
; #pragma unroll
;     for (int e = 0; e < 16; ++e) {
;       rhs[rl * 256 + cg8 * 16 + e] = vf[e] * bt;
;       rhs[rl * 256 + 128 + cg8 * 16 + e] = kf[e] * bt * eg;
;     }
;   }
;   {
;     const bfraw* kh = (const bfraw*)(sm + L_W);
;     const bfraw* ah = (w < 4) ? kh : (const bfraw*)(sm + L_QG);
;     const int mt = w & 3;
;     f32x4 acc[4];
; #pragma unroll
;     for (int i = 0; i < 4; ++i) acc[i] = (f32x4){0.f, 0.f, 0.f, 0.f};
; #pragma unroll
;     for (int kk = 0; kk < 4; ++kk) {
;       bf16x8 af = *(const bf16x8*)(ah + (mt * 16 + r) * 136 + kk * 32 + q * 8);
; #pragma unroll
;       for (int nt = 0; nt < 4; ++nt) {
;         bf16x8 bfr = *(const bf16x8*)(kh + (nt * 16 + r) * 136 + kk * 32 + q * 8);
;         acc[nt] = mfma16(af, bfr, acc[nt]);
;       }
;     }
;     float* Mm = (float*)(sm + L_MM);
;     bfraw* qk = (bfraw*)(sm + L_QK);
; #pragma unroll
;     for (int nt = 0; nt < 4; ++nt)
; #pragma unroll
;       for (int g = 0; g < 4; ++g) {
;         const int i = mt * 16 + q * 4 + g, j = nt * 16 + r;
;         const float Gi = misc[i], Gj = misc[j];
.LBB0_919:
	s_or_b64 exec, exec, s[0:1]
	v_mul_lo_u32 v16, v63, s46
	v_lshlrev_b32_e32 v17, 1, v162
	v_add3_u32 v34, 0, v16, v17
	v_cvt_pk_bf16_f32 v19, v70, v71
	v_cvt_pk_bf16_f32 v18, v74, v75
	v_cvt_pk_bf16_f32 v17, v78, v79
	v_cvt_pk_bf16_f32 v16, v82, v83
	ds_write_b128 v34, v[16:19] offset:17408
	v_cvt_pk_bf16_f32 v19, v68, v69
	v_cvt_pk_bf16_f32 v18, v72, v73
	v_cvt_pk_bf16_f32 v17, v76, v77
	v_cvt_pk_bf16_f32 v16, v80, v81
	ds_write_b128 v34, v[16:19] offset:17424
	v_cvt_pk_bf16_f32 v19, v92, v93
	v_cvt_pk_bf16_f32 v18, v94, v95
	v_cvt_pk_bf16_f32 v17, v96, v97
	v_cvt_pk_bf16_f32 v16, v66, v67
	ds_write_b128 v34, v[16:19]
	v_cvt_pk_bf16_f32 v19, v84, v85
	v_cvt_pk_bf16_f32 v18, v86, v87
	v_cvt_pk_bf16_f32 v17, v88, v89
	v_cvt_pk_bf16_f32 v16, v90, v91
	v_lshl_add_u32 v35, v63, 2, s33
	ds_write_b128 v34, v[16:19] offset:16
	s_waitcnt lgkmcnt(0)
	s_barrier
	ds_read2st64_b32 v[20:21], v35 offset0:1 offset1:2
	v_lshlrev_b32_e32 v16, 10, v63
	v_add3_u32 v23, s89, v16, v60
	v_ashrrev_i32_e32 v38, 6, v64
	v_and_b32_e32 v39, 15, v64
	s_waitcnt lgkmcnt(0)
	v_pk_mul_f32 v[0:1], v[0:1], v[20:21] op_sel_hi:[1,0]
	v_pk_mul_f32 v[2:3], v[2:3], v[20:21] op_sel_hi:[1,0]
	v_mov_b32_e32 v22, v21
	ds_write_b128 v23, v[0:3]
	v_pk_mul_f32 v[0:1], v[96:97], v[20:21] op_sel_hi:[1,0]
	v_pk_mul_f32 v[2:3], v[94:95], v[20:21] op_sel_hi:[1,0]
	v_pk_mul_f32 v[18:19], v[22:23], v[0:1] op_sel_hi:[0,1]
	v_pk_mul_f32 v[0:1], v[4:5], v[20:21] op_sel_hi:[1,0]
	v_pk_mul_f32 v[4:5], v[22:23], v[2:3] op_sel_hi:[0,1]
	v_pk_mul_f32 v[2:3], v[6:7], v[20:21] op_sel_hi:[1,0]
	ds_write_b128 v23, v[0:3] offset:16
	v_pk_mul_f32 v[0:1], v[92:93], v[20:21] op_sel_hi:[1,0]
	v_pk_mul_f32 v[2:3], v[90:91], v[20:21] op_sel_hi:[1,0]
	v_pk_mul_f32 v[6:7], v[22:23], v[0:1] op_sel_hi:[0,1]
	ds_write_b128 v23, v[4:7] offset:528
	v_pk_mul_f32 v[0:1], v[8:9], v[20:21] op_sel_hi:[1,0]
	v_pk_mul_f32 v[4:5], v[22:23], v[2:3] op_sel_hi:[0,1]
	v_pk_mul_f32 v[2:3], v[12:13], v[20:21] op_sel_hi:[1,0]
	ds_write_b128 v23, v[0:3] offset:32
	v_pk_mul_f32 v[0:1], v[88:89], v[20:21] op_sel_hi:[1,0]
	v_pk_mul_f32 v[2:3], v[86:87], v[20:21] op_sel_hi:[1,0]
	v_pk_mul_f32 v[6:7], v[22:23], v[0:1] op_sel_hi:[0,1]
	ds_write_b128 v23, v[4:7] offset:544
	v_pk_mul_f32 v[0:1], v[14:15], v[20:21] op_sel_hi:[1,0]
	v_pk_mul_f32 v[4:5], v[22:23], v[2:3] op_sel_hi:[0,1]
	v_pk_mul_f32 v[2:3], v[10:11], v[20:21] op_sel_hi:[1,0]
	v_pk_mul_f32 v[16:17], v[66:67], v[20:21] op_sel_hi:[1,0]
	ds_write_b128 v23, v[0:3] offset:48
	v_pk_mul_f32 v[0:1], v[84:85], v[20:21] op_sel_hi:[1,0]
	v_pk_mul_f32 v[16:17], v[22:23], v[16:17] op_sel_hi:[0,1]
	v_pk_mul_f32 v[6:7], v[22:23], v[0:1] op_sel_hi:[0,1]
	v_lshlrev_b32_e32 v1, 4, v38
	ds_write_b128 v23, v[16:19] offset:512
	v_and_b32_e32 v16, 48, v1
	v_cmp_gt_i32_e64 s[2:3], 4, v38
	v_mov_b32_e32 v0, s47
	v_or_b32_e32 v1, v16, v39
	v_cndmask_b32_e64 v0, v0, 0, s[2:3]
	v_mul_u32_u24_e32 v1, 0x110, v1
	v_and_b32_e32 v2, 48, v163
	ds_write_b128 v23, v[4:7] offset:560
	v_add3_u32 v17, v0, v1, v2
	v_add_u32_e32 v19, 0, v2
	ds_read_b128 v[0:3], v17
	v_mad_u32_u24 v18, v39, s46, v19
	ds_read_b128 v[4:7], v18
	ds_read_b128 v[8:11], v18 offset:4352
	ds_read_b128 v[12:15], v18 offset:8704
	ds_read_b128 v[20:23], v18 offset:13056
	s_waitcnt lgkmcnt(3)
	v_mfma_f32_16x16x32_bf16 v[4:7], v[0:3], v[4:7], 0
	v_lshrrev_b32_e32 v27, 4, v163
	v_lshl_or_b32 v16, v27, 2, v16
	v_cmp_lt_i32_e32 vcc, 3, v38
	s_waitcnt lgkmcnt(2)
	v_mfma_f32_16x16x32_bf16 v[8:11], v[0:3], v[8:11], 0
	s_waitcnt lgkmcnt(1)
	v_mfma_f32_16x16x32_bf16 v[12:15], v[0:3], v[12:15], 0
	s_waitcnt lgkmcnt(0)
	v_mfma_f32_16x16x32_bf16 v[0:3], v[0:3], v[20:23], 0
	ds_read_b128 v[20:23], v17 offset:64
	ds_read_b128 v[28:31], v18 offset:64
	s_waitcnt lgkmcnt(0)
	v_mfma_f32_16x16x32_bf16 v[4:7], v[20:23], v[28:31], v[4:7]
	ds_read_b128 v[28:31], v18 offset:4416
	s_waitcnt lgkmcnt(0)
	v_mfma_f32_16x16x32_bf16 v[8:11], v[20:23], v[28:31], v[8:11]
	ds_read_b128 v[28:31], v18 offset:8768
	s_waitcnt lgkmcnt(0)
	v_mfma_f32_16x16x32_bf16 v[12:15], v[20:23], v[28:31], v[12:15]
	ds_read_b128 v[28:31], v18 offset:13120
	s_waitcnt lgkmcnt(0)
	v_mfma_f32_16x16x32_bf16 v[0:3], v[20:23], v[28:31], v[0:3]
	ds_read_b128 v[20:23], v17 offset:128
	ds_read_b128 v[28:31], v18 offset:128
	s_waitcnt lgkmcnt(0)
	v_mfma_f32_16x16x32_bf16 v[4:7], v[20:23], v[28:31], v[4:7]
	ds_read_b128 v[28:31], v18 offset:4480
	s_waitcnt lgkmcnt(0)
	v_mfma_f32_16x16x32_bf16 v[8:11], v[20:23], v[28:31], v[8:11]
	ds_read_b128 v[28:31], v18 offset:8832
	s_waitcnt lgkmcnt(0)
	v_mfma_f32_16x16x32_bf16 v[28:31], v[20:23], v[28:31], v[12:15]
	s_nop 2
	ds_read_b128 v[12:15], v18 offset:13184
	s_waitcnt lgkmcnt(0)
	v_mfma_f32_16x16x32_bf16 v[0:3], v[20:23], v[12:15], v[0:3]
	ds_read_b128 v[20:23], v17 offset:192
	ds_read_b128 v[12:15], v18 offset:192
	v_lshl_add_u32 v17, v39, 1, 0
	s_waitcnt lgkmcnt(0)
	v_mfma_f32_16x16x32_bf16 v[12:15], v[20:23], v[12:15], v[4:7]
	s_nop 2
	ds_read_b128 v[4:7], v18 offset:4544
	s_waitcnt lgkmcnt(0)
	v_mfma_f32_16x16x32_bf16 v[8:11], v[20:23], v[4:7], v[8:11]
	ds_read_b128 v[4:7], v18 offset:8896
	s_waitcnt lgkmcnt(0)
	v_mfma_f32_16x16x32_bf16 v[4:7], v[20:23], v[4:7], v[28:31]
	s_nop 2
	ds_read_b128 v[28:31], v18 offset:13248
	v_lshl_add_u32 v18, v39, 2, s33
	s_waitcnt lgkmcnt(0)
	v_mfma_f32_16x16x32_bf16 v[0:3], v[20:23], v[28:31], v[0:3]
	v_and_b32_e32 v184, 15, v224
	v_bfe_u32 v185, v224, 4, 2
	v_lshrrev_b32_e32 v186, 6, v224
	v_and_b32_e32 v187, 3, v186
	v_lshlrev_b32_e32 v188, 2, v185
	v_lshl_add_u32 v188, v187, 4, v188
	v_lshlrev_b32_e32 v189, 2, v188
	v_add_u32_e32 v189, 0x27c00, v189
	v_lshlrev_b32_e32 v190, 2, v184
	v_add_u32_e32 v190, 0x27c00, v190
	ds_read_b128 v[192:195], v189
	ds_read_b128 v[196:199], v189 offset:256
	ds_read_b32 v200, v190
	ds_read_b32 v201, v190 offset:64
	ds_read_b32 v202, v190 offset:128
	ds_read_b32 v203, v190 offset:192
	v_add_u32_e32 v204, 0, v188
	v_add_u32_e32 v205, 1, v188
	v_add_u32_e32 v206, 2, v188
	v_add_u32_e32 v207, 3, v188
	v_add_u32_e32 v208, 0, v184
	v_add_u32_e32 v209, 16, v184
	v_add_u32_e32 v210, 32, v184
	v_add_u32_e32 v211, 48, v184
	v_readfirstlane_b32 s98, v186
	s_nop 7
	s_nop 7
	s_waitcnt lgkmcnt(0)
	s_cmp_lt_u32 s98, 4
	s_cbranch_scc0 .Lkk0_qk
; __device__ __forceinline__ float delta_prep(const Params& p, int l, int h, bool isP, int grow0, int t0, int nvalid, int bb, char* sm) {
;     ...
;     float* Mm = (float*)(sm + L_MM);
;     bfraw* qk = (bfraw*)(sm + L_QK);
; #pragma unroll
;     for (int nt = 0; nt < 4; ++nt)
; #pragma unroll
;       for (int g = 0; g < 4; ++g) {
;         const int i = mt * 16 + q * 4 + g, j = nt * 16 + r;
;         const float Gi = misc[i], Gj = misc[j];
;         if (w < 4) {
;           float v = (j < i) ? acc[nt][g] * __expf(Gi - Gj) * misc[64 + i] : 0.f;
;           Mm[j * 64 + i] = v;
;           ((bfraw*)(sm + L_KGT))[i * 72 + j] = f2bf(v);
	v_lshlrev_b32_e32 v212, 8, v184
	v_lshl_add_u32 v212, v188, 2, v212
	v_add_u32_e32 v212, 0x23c00, v212
	v_mul_u32_u24_e32 v213, 0x90, v188
	v_lshl_add_u32 v213, v184, 1, v213
	v_sub_f32_e32 v214, v192, v200
	v_mul_f32_e32 v214, 0x3fb8aa3b, v214
	v_exp_f32_e32 v215, v214
	v_cmp_lt_u32_e32 vcc, v208, v204
	v_mul_f32_e32 v216, v12, v215
	v_mul_f32_e32 v216, v216, v196
	v_cndmask_b32_e32 v220, 0, v216, vcc
	v_sub_f32_e32 v214, v193, v200
	v_mul_f32_e32 v214, 0x3fb8aa3b, v214
	v_exp_f32_e32 v215, v214
	v_cmp_lt_u32_e32 vcc, v208, v205
	v_mul_f32_e32 v216, v13, v215
	v_mul_f32_e32 v216, v216, v197
	v_cndmask_b32_e32 v221, 0, v216, vcc
	v_sub_f32_e32 v214, v194, v200
	v_mul_f32_e32 v214, 0x3fb8aa3b, v214
	v_exp_f32_e32 v215, v214
	v_cmp_lt_u32_e32 vcc, v208, v206
	v_mul_f32_e32 v216, v14, v215
	v_mul_f32_e32 v216, v216, v198
	v_cndmask_b32_e32 v222, 0, v216, vcc
	v_sub_f32_e32 v214, v195, v200
	v_mul_f32_e32 v214, 0x3fb8aa3b, v214
	v_exp_f32_e32 v215, v214
	v_cmp_lt_u32_e32 vcc, v208, v207
	v_mul_f32_e32 v216, v15, v215
	v_mul_f32_e32 v216, v216, v199
	v_cndmask_b32_e32 v223, 0, v216, vcc
	ds_write_b128 v212, v[220:223] offset:0
	v_cvt_pk_bf16_f32 v216, v220, v220
	ds_write_b16 v213, v216 offset:34816
	v_cvt_pk_bf16_f32 v216, v221, v221
	ds_write_b16 v213, v216 offset:34960
	v_cvt_pk_bf16_f32 v216, v222, v222
	ds_write_b16 v213, v216 offset:35104
	v_cvt_pk_bf16_f32 v216, v223, v223
	ds_write_b16 v213, v216 offset:35248
	v_sub_f32_e32 v214, v192, v201
	v_mul_f32_e32 v214, 0x3fb8aa3b, v214
	v_exp_f32_e32 v215, v214
	v_cmp_lt_u32_e32 vcc, v209, v204
	v_mul_f32_e32 v216, v8, v215
	v_mul_f32_e32 v216, v216, v196
	v_cndmask_b32_e32 v220, 0, v216, vcc
	v_sub_f32_e32 v214, v193, v201
	v_mul_f32_e32 v214, 0x3fb8aa3b, v214
	v_exp_f32_e32 v215, v214
	v_cmp_lt_u32_e32 vcc, v209, v205
	v_mul_f32_e32 v216, v9, v215
	v_mul_f32_e32 v216, v216, v197
	v_cndmask_b32_e32 v221, 0, v216, vcc
	v_sub_f32_e32 v214, v194, v201
	v_mul_f32_e32 v214, 0x3fb8aa3b, v214
	v_exp_f32_e32 v215, v214
	v_cmp_lt_u32_e32 vcc, v209, v206
	v_mul_f32_e32 v216, v10, v215
	v_mul_f32_e32 v216, v216, v198
	v_cndmask_b32_e32 v222, 0, v216, vcc
	v_sub_f32_e32 v214, v195, v201
	v_mul_f32_e32 v214, 0x3fb8aa3b, v214
	v_exp_f32_e32 v215, v214
	v_cmp_lt_u32_e32 vcc, v209, v207
	v_mul_f32_e32 v216, v11, v215
	v_mul_f32_e32 v216, v216, v199
	v_cndmask_b32_e32 v223, 0, v216, vcc
	ds_write_b128 v212, v[220:223] offset:4096
	v_cvt_pk_bf16_f32 v216, v220, v220
	ds_write_b16 v213, v216 offset:34848
	v_cvt_pk_bf16_f32 v216, v221, v221
	ds_write_b16 v213, v216 offset:34992
	v_cvt_pk_bf16_f32 v216, v222, v222
	ds_write_b16 v213, v216 offset:35136
	v_cvt_pk_bf16_f32 v216, v223, v223
	ds_write_b16 v213, v216 offset:35280
	v_sub_f32_e32 v214, v192, v202
	v_mul_f32_e32 v214, 0x3fb8aa3b, v214
	v_exp_f32_e32 v215, v214
	v_cmp_lt_u32_e32 vcc, v210, v204
	v_mul_f32_e32 v216, v4, v215
	v_mul_f32_e32 v216, v216, v196
	v_cndmask_b32_e32 v220, 0, v216, vcc
	v_sub_f32_e32 v214, v193, v202
	v_mul_f32_e32 v214, 0x3fb8aa3b, v214
	v_exp_f32_e32 v215, v214
	v_cmp_lt_u32_e32 vcc, v210, v205
	v_mul_f32_e32 v216, v5, v215
	v_mul_f32_e32 v216, v216, v197
	v_cndmask_b32_e32 v221, 0, v216, vcc
	v_sub_f32_e32 v214, v194, v202
	v_mul_f32_e32 v214, 0x3fb8aa3b, v214
	v_exp_f32_e32 v215, v214
	v_cmp_lt_u32_e32 vcc, v210, v206
	v_mul_f32_e32 v216, v6, v215
	v_mul_f32_e32 v216, v216, v198
	v_cndmask_b32_e32 v222, 0, v216, vcc
	v_sub_f32_e32 v214, v195, v202
	v_mul_f32_e32 v214, 0x3fb8aa3b, v214
	v_exp_f32_e32 v215, v214
	v_cmp_lt_u32_e32 vcc, v210, v207
	v_mul_f32_e32 v216, v7, v215
	v_mul_f32_e32 v216, v216, v199
	v_cndmask_b32_e32 v223, 0, v216, vcc
	ds_write_b128 v212, v[220:223] offset:8192
	v_cvt_pk_bf16_f32 v216, v220, v220
	ds_write_b16 v213, v216 offset:34880
	v_cvt_pk_bf16_f32 v216, v221, v221
	ds_write_b16 v213, v216 offset:35024
	v_cvt_pk_bf16_f32 v216, v222, v222
	ds_write_b16 v213, v216 offset:35168
	v_cvt_pk_bf16_f32 v216, v223, v223
	ds_write_b16 v213, v216 offset:35312
	v_sub_f32_e32 v214, v192, v203
	v_mul_f32_e32 v214, 0x3fb8aa3b, v214
	v_exp_f32_e32 v215, v214
	v_cmp_lt_u32_e32 vcc, v211, v204
	v_mul_f32_e32 v216, v0, v215
	v_mul_f32_e32 v216, v216, v196
	v_cndmask_b32_e32 v220, 0, v216, vcc
	v_sub_f32_e32 v214, v193, v203
	v_mul_f32_e32 v214, 0x3fb8aa3b, v214
	v_exp_f32_e32 v215, v214
	v_cmp_lt_u32_e32 vcc, v211, v205
	v_mul_f32_e32 v216, v1, v215
	v_mul_f32_e32 v216, v216, v197
	v_cndmask_b32_e32 v221, 0, v216, vcc
	v_sub_f32_e32 v214, v194, v203
	v_mul_f32_e32 v214, 0x3fb8aa3b, v214
	v_exp_f32_e32 v215, v214
	v_cmp_lt_u32_e32 vcc, v211, v206
	v_mul_f32_e32 v216, v2, v215
	v_mul_f32_e32 v216, v216, v198
	v_cndmask_b32_e32 v222, 0, v216, vcc
	v_sub_f32_e32 v214, v195, v203
	v_mul_f32_e32 v214, 0x3fb8aa3b, v214
	v_exp_f32_e32 v215, v214
	v_cmp_lt_u32_e32 vcc, v211, v207
	v_mul_f32_e32 v216, v3, v215
	v_mul_f32_e32 v216, v216, v199
	v_cndmask_b32_e32 v223, 0, v216, vcc
	ds_write_b128 v212, v[220:223] offset:12288
	v_cvt_pk_bf16_f32 v216, v220, v220
	ds_write_b16 v213, v216 offset:34912
	v_cvt_pk_bf16_f32 v216, v221, v221
	ds_write_b16 v213, v216 offset:35056
	v_cvt_pk_bf16_f32 v216, v222, v222
	ds_write_b16 v213, v216 offset:35200
	v_cvt_pk_bf16_f32 v216, v223, v223
	ds_write_b16 v213, v216 offset:35344
	s_branch .Lkk0_end
; __device__ __forceinline__ float delta_prep(const Params& p, int l, int h, bool isP, int grow0, int t0, int nvalid, int bb, char* sm) {
;     ...
;         } else {
;           float v = (j <= i) ? acc[nt][g] * __expf(Gi - Gj) : 0.f;
;           qk[i * 72 + j] = f2bf(v);
;         }
;       }
;   }
;   __syncthreads();
;   bfraw* XTu = (bfraw*)(sm + L_UT);
;   bfraw* XTw = (bfraw*)(sm + L_W);
;   {
;     const uint4 z4 = make_uint4(0u, 0u, 0u, 0u);
;     for (int c = tid; c < 128 * 9; c += NTHR) { *(uint4*)(XTu + c * 8) = z4; *(uint4*)(XTw + c * 8) = z4; }
;   }
.Lkk0_qk:
	v_mul_u32_u24_e32 v213, 0x90, v188
	v_lshl_add_u32 v213, v184, 1, v213
	v_sub_f32_e32 v214, v192, v200
	v_mul_f32_e32 v214, 0x3fb8aa3b, v214
	v_exp_f32_e32 v215, v214
	v_cmp_le_u32_e32 vcc, v208, v204
	v_mul_f32_e32 v216, v12, v215
	v_cvt_pk_bf16_f32 v216, v216, v216
	v_cndmask_b32_e32 v216, 0, v216, vcc
	ds_write_b16 v213, v216 offset:53248
	v_sub_f32_e32 v214, v193, v200
	v_mul_f32_e32 v214, 0x3fb8aa3b, v214
	v_exp_f32_e32 v215, v214
	v_cmp_le_u32_e32 vcc, v208, v205
	v_mul_f32_e32 v216, v13, v215
	v_cvt_pk_bf16_f32 v216, v216, v216
	v_cndmask_b32_e32 v216, 0, v216, vcc
	ds_write_b16 v213, v216 offset:53392
	v_sub_f32_e32 v214, v194, v200
	v_mul_f32_e32 v214, 0x3fb8aa3b, v214
	v_exp_f32_e32 v215, v214
	v_cmp_le_u32_e32 vcc, v208, v206
	v_mul_f32_e32 v216, v14, v215
	v_cvt_pk_bf16_f32 v216, v216, v216
	v_cndmask_b32_e32 v216, 0, v216, vcc
	ds_write_b16 v213, v216 offset:53536
	v_sub_f32_e32 v214, v195, v200
	v_mul_f32_e32 v214, 0x3fb8aa3b, v214
	v_exp_f32_e32 v215, v214
	v_cmp_le_u32_e32 vcc, v208, v207
	v_mul_f32_e32 v216, v15, v215
	v_cvt_pk_bf16_f32 v216, v216, v216
	v_cndmask_b32_e32 v216, 0, v216, vcc
	ds_write_b16 v213, v216 offset:53680
	v_sub_f32_e32 v214, v192, v201
	v_mul_f32_e32 v214, 0x3fb8aa3b, v214
	v_exp_f32_e32 v215, v214
	v_cmp_le_u32_e32 vcc, v209, v204
	v_mul_f32_e32 v216, v8, v215
	v_cvt_pk_bf16_f32 v216, v216, v216
	v_cndmask_b32_e32 v216, 0, v216, vcc
	ds_write_b16 v213, v216 offset:53280
	v_sub_f32_e32 v214, v193, v201
	v_mul_f32_e32 v214, 0x3fb8aa3b, v214
	v_exp_f32_e32 v215, v214
	v_cmp_le_u32_e32 vcc, v209, v205
	v_mul_f32_e32 v216, v9, v215
	v_cvt_pk_bf16_f32 v216, v216, v216
	v_cndmask_b32_e32 v216, 0, v216, vcc
	ds_write_b16 v213, v216 offset:53424
	v_sub_f32_e32 v214, v194, v201
	v_mul_f32_e32 v214, 0x3fb8aa3b, v214
	v_exp_f32_e32 v215, v214
	v_cmp_le_u32_e32 vcc, v209, v206
	v_mul_f32_e32 v216, v10, v215
	v_cvt_pk_bf16_f32 v216, v216, v216
	v_cndmask_b32_e32 v216, 0, v216, vcc
	ds_write_b16 v213, v216 offset:53568
	v_sub_f32_e32 v214, v195, v201
	v_mul_f32_e32 v214, 0x3fb8aa3b, v214
	v_exp_f32_e32 v215, v214
	v_cmp_le_u32_e32 vcc, v209, v207
	v_mul_f32_e32 v216, v11, v215
	v_cvt_pk_bf16_f32 v216, v216, v216
	v_cndmask_b32_e32 v216, 0, v216, vcc
	ds_write_b16 v213, v216 offset:53712
	v_sub_f32_e32 v214, v192, v202
	v_mul_f32_e32 v214, 0x3fb8aa3b, v214
	v_exp_f32_e32 v215, v214
	v_cmp_le_u32_e32 vcc, v210, v204
	v_mul_f32_e32 v216, v4, v215
	v_cvt_pk_bf16_f32 v216, v216, v216
	v_cndmask_b32_e32 v216, 0, v216, vcc
	ds_write_b16 v213, v216 offset:53312
	v_sub_f32_e32 v214, v193, v202
	v_mul_f32_e32 v214, 0x3fb8aa3b, v214
	v_exp_f32_e32 v215, v214
	v_cmp_le_u32_e32 vcc, v210, v205
	v_mul_f32_e32 v216, v5, v215
	v_cvt_pk_bf16_f32 v216, v216, v216
	v_cndmask_b32_e32 v216, 0, v216, vcc
	ds_write_b16 v213, v216 offset:53456
	v_sub_f32_e32 v214, v194, v202
	v_mul_f32_e32 v214, 0x3fb8aa3b, v214
	v_exp_f32_e32 v215, v214
	v_cmp_le_u32_e32 vcc, v210, v206
	v_mul_f32_e32 v216, v6, v215
	v_cvt_pk_bf16_f32 v216, v216, v216
	v_cndmask_b32_e32 v216, 0, v216, vcc
	ds_write_b16 v213, v216 offset:53600
	v_sub_f32_e32 v214, v195, v202
	v_mul_f32_e32 v214, 0x3fb8aa3b, v214
	v_exp_f32_e32 v215, v214
	v_cmp_le_u32_e32 vcc, v210, v207
	v_mul_f32_e32 v216, v7, v215
	v_cvt_pk_bf16_f32 v216, v216, v216
	v_cndmask_b32_e32 v216, 0, v216, vcc
	ds_write_b16 v213, v216 offset:53744
	v_sub_f32_e32 v214, v192, v203
	v_mul_f32_e32 v214, 0x3fb8aa3b, v214
	v_exp_f32_e32 v215, v214
	v_cmp_le_u32_e32 vcc, v211, v204
	v_mul_f32_e32 v216, v0, v215
	v_cvt_pk_bf16_f32 v216, v216, v216
	v_cndmask_b32_e32 v216, 0, v216, vcc
	ds_write_b16 v213, v216 offset:53344
	v_sub_f32_e32 v214, v193, v203
	v_mul_f32_e32 v214, 0x3fb8aa3b, v214
	v_exp_f32_e32 v215, v214
	v_cmp_le_u32_e32 vcc, v211, v205
	v_mul_f32_e32 v216, v1, v215
	v_cvt_pk_bf16_f32 v216, v216, v216
	v_cndmask_b32_e32 v216, 0, v216, vcc
	ds_write_b16 v213, v216 offset:53488
	v_sub_f32_e32 v214, v194, v203
	v_mul_f32_e32 v214, 0x3fb8aa3b, v214
	v_exp_f32_e32 v215, v214
	v_cmp_le_u32_e32 vcc, v211, v206
	v_mul_f32_e32 v216, v2, v215
	v_cvt_pk_bf16_f32 v216, v216, v216
	v_cndmask_b32_e32 v216, 0, v216, vcc
	ds_write_b16 v213, v216 offset:53632
	v_sub_f32_e32 v214, v195, v203
	v_mul_f32_e32 v214, 0x3fb8aa3b, v214
	v_exp_f32_e32 v215, v214
	v_cmp_le_u32_e32 vcc, v211, v207
	v_mul_f32_e32 v216, v3, v215
	v_cvt_pk_bf16_f32 v216, v216, v216
	v_cndmask_b32_e32 v216, 0, v216, vcc
	ds_write_b16 v213, v216 offset:53776
.Lkk0_end:
	v_lshlrev_b32_e32 v41, 3, v27
	v_or_b32_e32 v42, 16, v39
	v_or_b32_e32 v37, 32, v39
	v_or_b32_e32 v11, 48, v39
	s_movk_i32 s0, 0x480
	v_cmp_gt_i32_e32 vcc, s0, v64
	s_waitcnt lgkmcnt(0)
	s_barrier
	s_and_saveexec_b64 s[0:1], vcc
	s_cbranch_execz .LBB0_1030
	v_max_i32_e32 v0, 0x280, v64
	v_sub_u32_e32 v0, v0, v64
	v_add_u32_e32 v1, 0x1ff, v0
	s_movk_i32 s4, 0x1ff
	v_cmp_lt_u32_e32 vcc, s4, v1
	s_mov_b64 s[6:7], -1
	v_mov_b32_e32 v0, v64
	s_and_saveexec_b64 s[4:5], vcc
	s_cbranch_execz .LBB0_1027
	v_lshrrev_b32_e32 v2, 9, v1
	v_add_u32_e32 v0, -1, v2
	v_lshrrev_b32_e32 v1, 1, v0
	v_add_u32_e32 v3, 1, v1
	v_cmp_lt_u32_e32 vcc, 5, v0
	v_mov_b64_e32 v[0:1], v[64:65]
	s_and_saveexec_b64 s[6:7], vcc
	s_cbranch_execz .LBB0_1021
	v_and_b32_e32 v4, -4, v3
	s_mov_b64 s[8:9], 0
	v_mov_b64_e32 v[0:1], v[64:65]

; __device__ __forceinline__ float delta_prep(const Params& p, int l, int h, bool isP, int grow0, int t0, int nvalid, int bb, char* sm) {
;     ...
;     bfraw* qh = (bfraw*)(sm + L_QG);
;     bfraw* kh = (bfraw*)(sm + L_W);
;     *(uint4*)(qh + rl * 136 + cg8 * 16) = pack8(qf); *(uint4*)(qh + rl * 136 + cg8 * 16 + 8) = pack8(qf + 8);
;     *(uint4*)(kh + rl * 136 + cg8 * 16) = pack8(kf); *(uint4*)(kh + rl * 136 + cg8 * 16 + 8) = pack8(kf + 8);
;   }
;   __syncthreads();
;   {
;     float* rhs = (float*)(sm + L_RHS);
;     const float bt = misc[64 + rl], eg = misc[128 + rl];
; #pragma unroll
;     for (int e = 0; e < 16; ++e) {
;       rhs[rl * 256 + cg8 * 16 + e] = vf[e] * bt;
;       rhs[rl * 256 + 128 + cg8 * 16 + e] = kf[e] * bt * eg;
;     }
;   }
;   {
;     const bfraw* kh = (const bfraw*)(sm + L_W);
;     const bfraw* ah = (w < 4) ? kh : (const bfraw*)(sm + L_QG);
;     const int mt = w & 3;
;     f32x4 acc[4];
; #pragma unroll
;     for (int i = 0; i < 4; ++i) acc[i] = (f32x4){0.f, 0.f, 0.f, 0.f};
; #pragma unroll
;     for (int kk = 0; kk < 4; ++kk) {
;       bf16x8 af = *(const bf16x8*)(ah + (mt * 16 + r) * 136 + kk * 32 + q * 8);
; #pragma unroll
;       for (int nt = 0; nt < 4; ++nt) {
;         bf16x8 bfr = *(const bf16x8*)(kh + (nt * 16 + r) * 136 + kk * 32 + q * 8);
;         acc[nt] = mfma16(af, bfr, acc[nt]);
;       }
;     }
;     float* Mm = (float*)(sm + L_MM);
;     bfraw* qk = (bfraw*)(sm + L_QK);
; #pragma unroll
;     for (int nt = 0; nt < 4; ++nt)
; #pragma unroll
;       for (int g = 0; g < 4; ++g) {
;         const int i = mt * 16 + q * 4 + g, j = nt * 16 + r;
;         const float Gi = misc[i], Gj = misc[j];
.LBB0_1350:
	s_or_b64 exec, exec, s[0:1]
	v_mul_lo_u32 v20, v3, s46
	v_lshlrev_b32_e32 v21, 1, v65
	v_add3_u32 v38, 0, v20, v21
	v_cvt_pk_bf16_f32 v23, v70, v71
	v_cvt_pk_bf16_f32 v22, v74, v75
	v_cvt_pk_bf16_f32 v21, v78, v79
	v_cvt_pk_bf16_f32 v20, v82, v83
	ds_write_b128 v38, v[20:23] offset:17408
	v_cvt_pk_bf16_f32 v23, v68, v69
	v_cvt_pk_bf16_f32 v22, v72, v73
	v_cvt_pk_bf16_f32 v21, v76, v77
	v_cvt_pk_bf16_f32 v20, v80, v81
	ds_write_b128 v38, v[20:23] offset:17424
	v_cvt_pk_bf16_f32 v23, v92, v93
	v_cvt_pk_bf16_f32 v22, v94, v95
	v_cvt_pk_bf16_f32 v21, v96, v97
	v_cvt_pk_bf16_f32 v20, v66, v67
	ds_write_b128 v38, v[20:23]
	v_cvt_pk_bf16_f32 v23, v84, v85
	v_cvt_pk_bf16_f32 v22, v86, v87
	v_cvt_pk_bf16_f32 v21, v88, v89
	v_cvt_pk_bf16_f32 v20, v90, v91
	v_lshl_add_u32 v39, v3, 2, s51
	ds_write_b128 v38, v[20:23] offset:16
	s_waitcnt lgkmcnt(0)
	s_barrier
	ds_read2st64_b32 v[26:27], v39 offset0:1 offset1:2
	v_lshlrev_b32_e32 v22, 10, v3
	v_add3_u32 v29, s44, v22, v98
	v_ashrrev_i32_e32 v21, 6, v0
	v_and_b32_e32 v20, 15, v0
	s_waitcnt lgkmcnt(0)
	v_pk_mul_f32 v[4:5], v[4:5], v[26:27] op_sel_hi:[1,0]
	v_pk_mul_f32 v[6:7], v[6:7], v[26:27] op_sel_hi:[1,0]
	v_mov_b32_e32 v28, v27
	ds_write_b128 v29, v[4:7]
	v_pk_mul_f32 v[4:5], v[96:97], v[26:27] op_sel_hi:[1,0]
	v_pk_mul_f32 v[6:7], v[94:95], v[26:27] op_sel_hi:[1,0]
	v_pk_mul_f32 v[24:25], v[28:29], v[4:5] op_sel_hi:[0,1]
	v_pk_mul_f32 v[4:5], v[8:9], v[26:27] op_sel_hi:[1,0]
	v_pk_mul_f32 v[8:9], v[28:29], v[6:7] op_sel_hi:[0,1]
	v_pk_mul_f32 v[6:7], v[10:11], v[26:27] op_sel_hi:[1,0]
	ds_write_b128 v29, v[4:7] offset:16
	v_pk_mul_f32 v[4:5], v[92:93], v[26:27] op_sel_hi:[1,0]
	v_pk_mul_f32 v[6:7], v[90:91], v[26:27] op_sel_hi:[1,0]
	v_pk_mul_f32 v[10:11], v[28:29], v[4:5] op_sel_hi:[0,1]
	ds_write_b128 v29, v[8:11] offset:528
	v_pk_mul_f32 v[4:5], v[12:13], v[26:27] op_sel_hi:[1,0]
	v_pk_mul_f32 v[8:9], v[28:29], v[6:7] op_sel_hi:[0,1]
	v_pk_mul_f32 v[6:7], v[16:17], v[26:27] op_sel_hi:[1,0]
	ds_write_b128 v29, v[4:7] offset:32
	v_pk_mul_f32 v[4:5], v[88:89], v[26:27] op_sel_hi:[1,0]
	v_pk_mul_f32 v[6:7], v[86:87], v[26:27] op_sel_hi:[1,0]
	v_pk_mul_f32 v[10:11], v[28:29], v[4:5] op_sel_hi:[0,1]
	ds_write_b128 v29, v[8:11] offset:544
	v_pk_mul_f32 v[4:5], v[18:19], v[26:27] op_sel_hi:[1,0]
	v_pk_mul_f32 v[8:9], v[28:29], v[6:7] op_sel_hi:[0,1]
	v_pk_mul_f32 v[6:7], v[14:15], v[26:27] op_sel_hi:[1,0]
	ds_write_b128 v29, v[4:7] offset:48
	v_pk_mul_f32 v[4:5], v[84:85], v[26:27] op_sel_hi:[1,0]
	v_lshlrev_b32_e32 v34, 4, v21
	v_pk_mul_f32 v[22:23], v[66:67], v[26:27] op_sel_hi:[1,0]
	v_pk_mul_f32 v[10:11], v[28:29], v[4:5] op_sel_hi:[0,1]
	v_cmp_gt_i32_e32 vcc, 4, v21
	v_mov_b32_e32 v4, s94
	v_and_or_b32 v5, v34, 48, v20
	v_pk_mul_f32 v[22:23], v[28:29], v[22:23] op_sel_hi:[0,1]
	ds_write_b128 v29, v[8:11] offset:560
	v_cndmask_b32_e64 v4, v4, 0, vcc
	v_mul_u32_u24_e32 v5, 0x110, v5
	v_and_b32_e32 v8, 48, v165
	ds_write_b128 v29, v[22:25] offset:512
	v_add3_u32 v35, v4, v5, v8
	ds_read_b128 v[4:7], v35
	v_mul_u32_u24_e32 v9, 0x110, v20
	v_add3_u32 v36, 0, v8, v9
	ds_read_b128 v[8:11], v36
	ds_read_b128 v[12:15], v36 offset:4352
	ds_read_b128 v[16:19], v36 offset:8704
	ds_read_b128 v[22:25], v36 offset:13056
	ds_read_b128 v[26:29], v35 offset:64
	s_waitcnt lgkmcnt(4)
	v_mfma_f32_16x16x32_bf16 v[8:11], v[4:7], v[8:11], 0
	v_cmp_lt_i32_e32 vcc, 3, v21
	v_lshrrev_b32_e32 v21, 2, v165
	v_bitop3_b32 v21, v34, 60, v21 bitop3:0xc8
	s_waitcnt lgkmcnt(3)
	v_mfma_f32_16x16x32_bf16 v[12:15], v[4:7], v[12:15], 0
	s_waitcnt lgkmcnt(2)
	v_mfma_f32_16x16x32_bf16 v[16:19], v[4:7], v[16:19], 0
	s_waitcnt lgkmcnt(1)
	v_mfma_f32_16x16x32_bf16 v[4:7], v[4:7], v[22:25], 0
	ds_read_b128 v[22:25], v36 offset:64
	s_waitcnt lgkmcnt(0)
	v_mfma_f32_16x16x32_bf16 v[8:11], v[26:29], v[22:25], v[8:11]
	ds_read_b128 v[22:25], v36 offset:4416
	s_waitcnt lgkmcnt(0)
	v_mfma_f32_16x16x32_bf16 v[12:15], v[26:29], v[22:25], v[12:15]
	ds_read_b128 v[22:25], v36 offset:8768
	ds_read_b128 v[30:33], v36 offset:13120
	s_waitcnt lgkmcnt(1)
	v_mfma_f32_16x16x32_bf16 v[16:19], v[26:29], v[22:25], v[16:19]
	ds_read_b128 v[22:25], v35 offset:128
	s_waitcnt lgkmcnt(1)
	v_mfma_f32_16x16x32_bf16 v[4:7], v[26:29], v[30:33], v[4:7]
	ds_read_b128 v[26:29], v36 offset:128
	s_waitcnt lgkmcnt(0)
	v_mfma_f32_16x16x32_bf16 v[8:11], v[22:25], v[26:29], v[8:11]
	ds_read_b128 v[26:29], v36 offset:4480
	s_waitcnt lgkmcnt(0)
	v_mfma_f32_16x16x32_bf16 v[12:15], v[22:25], v[26:29], v[12:15]
	ds_read_b128 v[26:29], v36 offset:8832
	ds_read_b128 v[30:33], v36 offset:13184
	ds_read_b128 v[40:43], v35 offset:192
	s_waitcnt lgkmcnt(2)
	v_mfma_f32_16x16x32_bf16 v[26:29], v[22:25], v[26:29], v[16:19]
	s_nop 2
	ds_read_b128 v[16:19], v36 offset:192
	s_waitcnt lgkmcnt(2)
	v_mfma_f32_16x16x32_bf16 v[4:7], v[22:25], v[30:33], v[4:7]
	ds_read_b128 v[22:25], v36 offset:13248
	s_waitcnt lgkmcnt(1)
	v_mfma_f32_16x16x32_bf16 v[16:19], v[40:43], v[16:19], v[8:11]
	s_nop 2
	ds_read_b128 v[8:11], v36 offset:4544
	s_waitcnt lgkmcnt(0)
	v_mfma_f32_16x16x32_bf16 v[12:15], v[40:43], v[8:11], v[12:15]
	ds_read_b128 v[8:11], v36 offset:8896
	s_waitcnt lgkmcnt(0)
	v_mfma_f32_16x16x32_bf16 v[8:11], v[40:43], v[8:11], v[26:29]
	s_nop 2
	v_lshl_add_u32 v27, v21, 2, s51
	v_lshl_add_u32 v26, v20, 2, s51
	ds_read_b32 v30, v27
	ds_read_b32 v37, v26
	v_mfma_f32_16x16x32_bf16 v[4:7], v[40:43], v[22:25], v[4:7]
	v_and_b32_e32 v184, 15, v224
	v_bfe_u32 v185, v224, 4, 2
	v_lshrrev_b32_e32 v186, 6, v224
	v_and_b32_e32 v187, 3, v186
	v_lshlrev_b32_e32 v188, 2, v185
	v_lshl_add_u32 v188, v187, 4, v188
	v_lshlrev_b32_e32 v189, 2, v188
	v_add_u32_e32 v189, 0x27c00, v189
	v_lshlrev_b32_e32 v190, 2, v184
	v_add_u32_e32 v190, 0x27c00, v190
	ds_read_b128 v[192:195], v189
	ds_read_b128 v[196:199], v189 offset:256
	ds_read_b32 v200, v190
	ds_read_b32 v201, v190 offset:64
	ds_read_b32 v202, v190 offset:128
	ds_read_b32 v203, v190 offset:192
	v_add_u32_e32 v204, 0, v188
	v_add_u32_e32 v205, 1, v188
	v_add_u32_e32 v206, 2, v188
	v_add_u32_e32 v207, 3, v188
	v_add_u32_e32 v208, 0, v184
	v_add_u32_e32 v209, 16, v184
	v_add_u32_e32 v210, 32, v184
	v_add_u32_e32 v211, 48, v184
	v_readfirstlane_b32 s98, v186
	s_nop 7
	s_nop 7
	s_waitcnt lgkmcnt(0)
	s_cmp_lt_u32 s98, 4
	s_cbranch_scc0 .Lkk1_qk
; __device__ __forceinline__ float delta_prep(const Params& p, int l, int h, bool isP, int grow0, int t0, int nvalid, int bb, char* sm) {
;     ...
;     float* Mm = (float*)(sm + L_MM);
;     bfraw* qk = (bfraw*)(sm + L_QK);
; #pragma unroll
;     for (int nt = 0; nt < 4; ++nt)
; #pragma unroll
;       for (int g = 0; g < 4; ++g) {
;         const int i = mt * 16 + q * 4 + g, j = nt * 16 + r;
;         const float Gi = misc[i], Gj = misc[j];
;         if (w < 4) {
;           float v = (j < i) ? acc[nt][g] * __expf(Gi - Gj) * misc[64 + i] : 0.f;
;           Mm[j * 64 + i] = v;
;           ((bfraw*)(sm + L_KGT))[i * 72 + j] = f2bf(v);
	v_lshlrev_b32_e32 v212, 8, v184
	v_lshl_add_u32 v212, v188, 2, v212
	v_add_u32_e32 v212, 0x23c00, v212
	v_mul_u32_u24_e32 v213, 0x90, v188
	v_lshl_add_u32 v213, v184, 1, v213
	v_sub_f32_e32 v214, v192, v200
	v_mul_f32_e32 v214, 0x3fb8aa3b, v214
	v_exp_f32_e32 v215, v214
	v_cmp_lt_u32_e32 vcc, v208, v204
	v_mul_f32_e32 v216, v16, v215
	v_mul_f32_e32 v216, v216, v196
	v_cndmask_b32_e32 v220, 0, v216, vcc
	v_sub_f32_e32 v214, v193, v200
	v_mul_f32_e32 v214, 0x3fb8aa3b, v214
	v_exp_f32_e32 v215, v214
	v_cmp_lt_u32_e32 vcc, v208, v205
	v_mul_f32_e32 v216, v17, v215
	v_mul_f32_e32 v216, v216, v197
	v_cndmask_b32_e32 v221, 0, v216, vcc
	v_sub_f32_e32 v214, v194, v200
	v_mul_f32_e32 v214, 0x3fb8aa3b, v214
	v_exp_f32_e32 v215, v214
	v_cmp_lt_u32_e32 vcc, v208, v206
	v_mul_f32_e32 v216, v18, v215
	v_mul_f32_e32 v216, v216, v198
	v_cndmask_b32_e32 v222, 0, v216, vcc
	v_sub_f32_e32 v214, v195, v200
	v_mul_f32_e32 v214, 0x3fb8aa3b, v214
	v_exp_f32_e32 v215, v214
	v_cmp_lt_u32_e32 vcc, v208, v207
	v_mul_f32_e32 v216, v19, v215
	v_mul_f32_e32 v216, v216, v199
	v_cndmask_b32_e32 v223, 0, v216, vcc
	ds_write_b128 v212, v[220:223] offset:0
	v_cvt_pk_bf16_f32 v216, v220, v220
	ds_write_b16 v213, v216 offset:34816
	v_cvt_pk_bf16_f32 v216, v221, v221
	ds_write_b16 v213, v216 offset:34960
	v_cvt_pk_bf16_f32 v216, v222, v222
	ds_write_b16 v213, v216 offset:35104
	v_cvt_pk_bf16_f32 v216, v223, v223
	ds_write_b16 v213, v216 offset:35248
	v_sub_f32_e32 v214, v192, v201
	v_mul_f32_e32 v214, 0x3fb8aa3b, v214
	v_exp_f32_e32 v215, v214
	v_cmp_lt_u32_e32 vcc, v209, v204
	v_mul_f32_e32 v216, v12, v215
	v_mul_f32_e32 v216, v216, v196
	v_cndmask_b32_e32 v220, 0, v216, vcc
	v_sub_f32_e32 v214, v193, v201
	v_mul_f32_e32 v214, 0x3fb8aa3b, v214
	v_exp_f32_e32 v215, v214
	v_cmp_lt_u32_e32 vcc, v209, v205
	v_mul_f32_e32 v216, v13, v215
	v_mul_f32_e32 v216, v216, v197
	v_cndmask_b32_e32 v221, 0, v216, vcc
	v_sub_f32_e32 v214, v194, v201
	v_mul_f32_e32 v214, 0x3fb8aa3b, v214
	v_exp_f32_e32 v215, v214
	v_cmp_lt_u32_e32 vcc, v209, v206
	v_mul_f32_e32 v216, v14, v215
	v_mul_f32_e32 v216, v216, v198
	v_cndmask_b32_e32 v222, 0, v216, vcc
	v_sub_f32_e32 v214, v195, v201
	v_mul_f32_e32 v214, 0x3fb8aa3b, v214
	v_exp_f32_e32 v215, v214
	v_cmp_lt_u32_e32 vcc, v209, v207
	v_mul_f32_e32 v216, v15, v215
	v_mul_f32_e32 v216, v216, v199
	v_cndmask_b32_e32 v223, 0, v216, vcc
	ds_write_b128 v212, v[220:223] offset:4096
	v_cvt_pk_bf16_f32 v216, v220, v220
	ds_write_b16 v213, v216 offset:34848
	v_cvt_pk_bf16_f32 v216, v221, v221
	ds_write_b16 v213, v216 offset:34992
	v_cvt_pk_bf16_f32 v216, v222, v222
	ds_write_b16 v213, v216 offset:35136
	v_cvt_pk_bf16_f32 v216, v223, v223
	ds_write_b16 v213, v216 offset:35280
	v_sub_f32_e32 v214, v192, v202
	v_mul_f32_e32 v214, 0x3fb8aa3b, v214
	v_exp_f32_e32 v215, v214
	v_cmp_lt_u32_e32 vcc, v210, v204
	v_mul_f32_e32 v216, v8, v215
	v_mul_f32_e32 v216, v216, v196
	v_cndmask_b32_e32 v220, 0, v216, vcc
	v_sub_f32_e32 v214, v193, v202
	v_mul_f32_e32 v214, 0x3fb8aa3b, v214
	v_exp_f32_e32 v215, v214
	v_cmp_lt_u32_e32 vcc, v210, v205
	v_mul_f32_e32 v216, v9, v215
	v_mul_f32_e32 v216, v216, v197
	v_cndmask_b32_e32 v221, 0, v216, vcc
	v_sub_f32_e32 v214, v194, v202
	v_mul_f32_e32 v214, 0x3fb8aa3b, v214
	v_exp_f32_e32 v215, v214
	v_cmp_lt_u32_e32 vcc, v210, v206
	v_mul_f32_e32 v216, v10, v215
	v_mul_f32_e32 v216, v216, v198
	v_cndmask_b32_e32 v222, 0, v216, vcc
	v_sub_f32_e32 v214, v195, v202
	v_mul_f32_e32 v214, 0x3fb8aa3b, v214
	v_exp_f32_e32 v215, v214
	v_cmp_lt_u32_e32 vcc, v210, v207
	v_mul_f32_e32 v216, v11, v215
	v_mul_f32_e32 v216, v216, v199
	v_cndmask_b32_e32 v223, 0, v216, vcc
	ds_write_b128 v212, v[220:223] offset:8192
	v_cvt_pk_bf16_f32 v216, v220, v220
	ds_write_b16 v213, v216 offset:34880
	v_cvt_pk_bf16_f32 v216, v221, v221
	ds_write_b16 v213, v216 offset:35024
	v_cvt_pk_bf16_f32 v216, v222, v222
	ds_write_b16 v213, v216 offset:35168
	v_cvt_pk_bf16_f32 v216, v223, v223
	ds_write_b16 v213, v216 offset:35312
	v_sub_f32_e32 v214, v192, v203
	v_mul_f32_e32 v214, 0x3fb8aa3b, v214
	v_exp_f32_e32 v215, v214
	v_cmp_lt_u32_e32 vcc, v211, v204
	v_mul_f32_e32 v216, v4, v215
	v_mul_f32_e32 v216, v216, v196
	v_cndmask_b32_e32 v220, 0, v216, vcc
	v_sub_f32_e32 v214, v193, v203
	v_mul_f32_e32 v214, 0x3fb8aa3b, v214
	v_exp_f32_e32 v215, v214
	v_cmp_lt_u32_e32 vcc, v211, v205
	v_mul_f32_e32 v216, v5, v215
	v_mul_f32_e32 v216, v216, v197
	v_cndmask_b32_e32 v221, 0, v216, vcc
	v_sub_f32_e32 v214, v194, v203
	v_mul_f32_e32 v214, 0x3fb8aa3b, v214
	v_exp_f32_e32 v215, v214
	v_cmp_lt_u32_e32 vcc, v211, v206
	v_mul_f32_e32 v216, v6, v215
	v_mul_f32_e32 v216, v216, v198
	v_cndmask_b32_e32 v222, 0, v216, vcc
	v_sub_f32_e32 v214, v195, v203
	v_mul_f32_e32 v214, 0x3fb8aa3b, v214
	v_exp_f32_e32 v215, v214
	v_cmp_lt_u32_e32 vcc, v211, v207
	v_mul_f32_e32 v216, v7, v215
	v_mul_f32_e32 v216, v216, v199
	v_cndmask_b32_e32 v223, 0, v216, vcc
	ds_write_b128 v212, v[220:223] offset:12288
	v_cvt_pk_bf16_f32 v216, v220, v220
	ds_write_b16 v213, v216 offset:34912
	v_cvt_pk_bf16_f32 v216, v221, v221
	ds_write_b16 v213, v216 offset:35056
	v_cvt_pk_bf16_f32 v216, v222, v222
	ds_write_b16 v213, v216 offset:35200
	v_cvt_pk_bf16_f32 v216, v223, v223
	ds_write_b16 v213, v216 offset:35344
	s_branch .Lkk1_end
; __device__ __forceinline__ float delta_prep(const Params& p, int l, int h, bool isP, int grow0, int t0, int nvalid, int bb, char* sm) {
;     ...
;         } else {
;           float v = (j <= i) ? acc[nt][g] * __expf(Gi - Gj) : 0.f;
;           qk[i * 72 + j] = f2bf(v);
;         }
;       }
;   }
;   __syncthreads();
;   bfraw* XTu = (bfraw*)(sm + L_UT);
;   bfraw* XTw = (bfraw*)(sm + L_W);
;   {
;     const uint4 z4 = make_uint4(0u, 0u, 0u, 0u);
;     for (int c = tid; c < 128 * 9; c += NTHR) { *(uint4*)(XTu + c * 8) = z4; *(uint4*)(XTw + c * 8) = z4; }
;   }
.Lkk1_qk:
	v_mul_u32_u24_e32 v213, 0x90, v188
	v_lshl_add_u32 v213, v184, 1, v213
	v_sub_f32_e32 v214, v192, v200
	v_mul_f32_e32 v214, 0x3fb8aa3b, v214
	v_exp_f32_e32 v215, v214
	v_cmp_le_u32_e32 vcc, v208, v204
	v_mul_f32_e32 v216, v16, v215
	v_cvt_pk_bf16_f32 v216, v216, v216
	v_cndmask_b32_e32 v216, 0, v216, vcc
	ds_write_b16 v213, v216 offset:53248
	v_sub_f32_e32 v214, v193, v200
	v_mul_f32_e32 v214, 0x3fb8aa3b, v214
	v_exp_f32_e32 v215, v214
	v_cmp_le_u32_e32 vcc, v208, v205
	v_mul_f32_e32 v216, v17, v215
	v_cvt_pk_bf16_f32 v216, v216, v216
	v_cndmask_b32_e32 v216, 0, v216, vcc
	ds_write_b16 v213, v216 offset:53392
	v_sub_f32_e32 v214, v194, v200
	v_mul_f32_e32 v214, 0x3fb8aa3b, v214
	v_exp_f32_e32 v215, v214
	v_cmp_le_u32_e32 vcc, v208, v206
	v_mul_f32_e32 v216, v18, v215
	v_cvt_pk_bf16_f32 v216, v216, v216
	v_cndmask_b32_e32 v216, 0, v216, vcc
	ds_write_b16 v213, v216 offset:53536
	v_sub_f32_e32 v214, v195, v200
	v_mul_f32_e32 v214, 0x3fb8aa3b, v214
	v_exp_f32_e32 v215, v214
	v_cmp_le_u32_e32 vcc, v208, v207
	v_mul_f32_e32 v216, v19, v215
	v_cvt_pk_bf16_f32 v216, v216, v216
	v_cndmask_b32_e32 v216, 0, v216, vcc
	ds_write_b16 v213, v216 offset:53680
	v_sub_f32_e32 v214, v192, v201
	v_mul_f32_e32 v214, 0x3fb8aa3b, v214
	v_exp_f32_e32 v215, v214
	v_cmp_le_u32_e32 vcc, v209, v204
	v_mul_f32_e32 v216, v12, v215
	v_cvt_pk_bf16_f32 v216, v216, v216
	v_cndmask_b32_e32 v216, 0, v216, vcc
	ds_write_b16 v213, v216 offset:53280
	v_sub_f32_e32 v214, v193, v201
	v_mul_f32_e32 v214, 0x3fb8aa3b, v214
	v_exp_f32_e32 v215, v214
	v_cmp_le_u32_e32 vcc, v209, v205
	v_mul_f32_e32 v216, v13, v215
	v_cvt_pk_bf16_f32 v216, v216, v216
	v_cndmask_b32_e32 v216, 0, v216, vcc
	ds_write_b16 v213, v216 offset:53424
	v_sub_f32_e32 v214, v194, v201
	v_mul_f32_e32 v214, 0x3fb8aa3b, v214
	v_exp_f32_e32 v215, v214
	v_cmp_le_u32_e32 vcc, v209, v206
	v_mul_f32_e32 v216, v14, v215
	v_cvt_pk_bf16_f32 v216, v216, v216
	v_cndmask_b32_e32 v216, 0, v216, vcc
	ds_write_b16 v213, v216 offset:53568
	v_sub_f32_e32 v214, v195, v201
	v_mul_f32_e32 v214, 0x3fb8aa3b, v214
	v_exp_f32_e32 v215, v214
	v_cmp_le_u32_e32 vcc, v209, v207
	v_mul_f32_e32 v216, v15, v215
	v_cvt_pk_bf16_f32 v216, v216, v216
	v_cndmask_b32_e32 v216, 0, v216, vcc
	ds_write_b16 v213, v216 offset:53712
	v_sub_f32_e32 v214, v192, v202
	v_mul_f32_e32 v214, 0x3fb8aa3b, v214
	v_exp_f32_e32 v215, v214
	v_cmp_le_u32_e32 vcc, v210, v204
	v_mul_f32_e32 v216, v8, v215
	v_cvt_pk_bf16_f32 v216, v216, v216
	v_cndmask_b32_e32 v216, 0, v216, vcc
	ds_write_b16 v213, v216 offset:53312
	v_sub_f32_e32 v214, v193, v202
	v_mul_f32_e32 v214, 0x3fb8aa3b, v214
	v_exp_f32_e32 v215, v214
	v_cmp_le_u32_e32 vcc, v210, v205
	v_mul_f32_e32 v216, v9, v215
	v_cvt_pk_bf16_f32 v216, v216, v216
	v_cndmask_b32_e32 v216, 0, v216, vcc
	ds_write_b16 v213, v216 offset:53456
	v_sub_f32_e32 v214, v194, v202
	v_mul_f32_e32 v214, 0x3fb8aa3b, v214
	v_exp_f32_e32 v215, v214
	v_cmp_le_u32_e32 vcc, v210, v206
	v_mul_f32_e32 v216, v10, v215
	v_cvt_pk_bf16_f32 v216, v216, v216
	v_cndmask_b32_e32 v216, 0, v216, vcc
	ds_write_b16 v213, v216 offset:53600
	v_sub_f32_e32 v214, v195, v202
	v_mul_f32_e32 v214, 0x3fb8aa3b, v214
	v_exp_f32_e32 v215, v214
	v_cmp_le_u32_e32 vcc, v210, v207
	v_mul_f32_e32 v216, v11, v215
	v_cvt_pk_bf16_f32 v216, v216, v216
	v_cndmask_b32_e32 v216, 0, v216, vcc
	ds_write_b16 v213, v216 offset:53744
	v_sub_f32_e32 v214, v192, v203
	v_mul_f32_e32 v214, 0x3fb8aa3b, v214
	v_exp_f32_e32 v215, v214
	v_cmp_le_u32_e32 vcc, v211, v204
	v_mul_f32_e32 v216, v4, v215
	v_cvt_pk_bf16_f32 v216, v216, v216
	v_cndmask_b32_e32 v216, 0, v216, vcc
	ds_write_b16 v213, v216 offset:53344
	v_sub_f32_e32 v214, v193, v203
	v_mul_f32_e32 v214, 0x3fb8aa3b, v214
	v_exp_f32_e32 v215, v214
	v_cmp_le_u32_e32 vcc, v211, v205
	v_mul_f32_e32 v216, v5, v215
	v_cvt_pk_bf16_f32 v216, v216, v216
	v_cndmask_b32_e32 v216, 0, v216, vcc
	ds_write_b16 v213, v216 offset:53488
	v_sub_f32_e32 v214, v194, v203
	v_mul_f32_e32 v214, 0x3fb8aa3b, v214
	v_exp_f32_e32 v215, v214
	v_cmp_le_u32_e32 vcc, v211, v206
	v_mul_f32_e32 v216, v6, v215
	v_cvt_pk_bf16_f32 v216, v216, v216
	v_cndmask_b32_e32 v216, 0, v216, vcc
	ds_write_b16 v213, v216 offset:53632
	v_sub_f32_e32 v214, v195, v203
	v_mul_f32_e32 v214, 0x3fb8aa3b, v214
	v_exp_f32_e32 v215, v214
	v_cmp_le_u32_e32 vcc, v211, v207
	v_mul_f32_e32 v216, v7, v215
	v_cvt_pk_bf16_f32 v216, v216, v216
	v_cndmask_b32_e32 v216, 0, v216, vcc
	ds_write_b16 v213, v216 offset:53776
.Lkk1_end:
	s_movk_i32 s0, 0x480
	v_cmp_gt_i32_e32 vcc, s0, v0
	s_waitcnt lgkmcnt(0)
	s_barrier
	s_and_saveexec_b64 s[0:1], vcc
	s_cbranch_execz .LBB0_1461
	v_max_i32_e32 v4, 0x280, v0
	v_sub_u32_e32 v4, v4, v0
	v_add_u32_e32 v5, 0x1ff, v4
	s_movk_i32 s2, 0x1ff
	v_cmp_lt_u32_e32 vcc, s2, v5
	s_mov_b64 s[4:5], -1
	v_mov_b32_e32 v4, v0
	s_and_saveexec_b64 s[2:3], vcc
	s_cbranch_execz .LBB0_1458
	v_lshrrev_b32_e32 v6, 9, v5
	v_add_u32_e32 v4, -1, v6
	v_lshrrev_b32_e32 v5, 1, v4
	v_add_u32_e32 v7, 1, v5
	v_cmp_lt_u32_e32 vcc, 5, v4
	v_mov_b64_e32 v[4:5], v[0:1]
	s_and_saveexec_b64 s[4:5], vcc
	s_cbranch_execz .LBB0_1452
	v_and_b32_e32 v8, -4, v7
	s_mov_b64 s[6:7], 0
	v_mov_b64_e32 v[4:5], v[0:1]

; __device__ __forceinline__ float delta_prep(const Params& p, int l, int h, bool isP, int grow0, int t0, int nvalid, int bb, char* sm) {
;     ...
;     bfraw* qh = (bfraw*)(sm + L_QG);
;     bfraw* kh = (bfraw*)(sm + L_W);
;     *(uint4*)(qh + rl * 136 + cg8 * 16) = pack8(qf); *(uint4*)(qh + rl * 136 + cg8 * 16 + 8) = pack8(qf + 8);
;     *(uint4*)(kh + rl * 136 + cg8 * 16) = pack8(kf); *(uint4*)(kh + rl * 136 + cg8 * 16 + 8) = pack8(kf + 8);
;   }
;   __syncthreads();
;   {
;     float* rhs = (float*)(sm + L_RHS);
;     const float bt = misc[64 + rl], eg = misc[128 + rl];
; #pragma unroll
;     for (int e = 0; e < 16; ++e) {
;       rhs[rl * 256 + cg8 * 16 + e] = vf[e] * bt;
;       rhs[rl * 256 + 128 + cg8 * 16 + e] = kf[e] * bt * eg;
;     }
;   }
;   {
;     const bfraw* kh = (const bfraw*)(sm + L_W);
;     const bfraw* ah = (w < 4) ? kh : (const bfraw*)(sm + L_QG);
;     const int mt = w & 3;
;     f32x4 acc[4];
; #pragma unroll
;     for (int i = 0; i < 4; ++i) acc[i] = (f32x4){0.f, 0.f, 0.f, 0.f};
; #pragma unroll
;     for (int kk = 0; kk < 4; ++kk) {
;       bf16x8 af = *(const bf16x8*)(ah + (mt * 16 + r) * 136 + kk * 32 + q * 8);
; #pragma unroll
;       for (int nt = 0; nt < 4; ++nt) {
;         bf16x8 bfr = *(const bf16x8*)(kh + (nt * 16 + r) * 136 + kk * 32 + q * 8);
;         acc[nt] = mfma16(af, bfr, acc[nt]);
;       }
;     }
;     float* Mm = (float*)(sm + L_MM);
;     bfraw* qk = (bfraw*)(sm + L_QK);
; #pragma unroll
;     for (int nt = 0; nt < 4; ++nt)
; #pragma unroll
;       for (int g = 0; g < 4; ++g) {
;         const int i = mt * 16 + q * 4 + g, j = nt * 16 + r;
;         const float Gi = misc[i], Gj = misc[j];
.LBB0_3677:
	s_or_b64 exec, exec, s[0:1]
	v_mul_lo_u32 v16, v63, s57
	v_lshlrev_b32_e32 v17, 1, v162
	v_add3_u32 v34, 0, v16, v17
	v_cvt_pk_bf16_f32 v19, v70, v71
	v_cvt_pk_bf16_f32 v18, v74, v75
	v_cvt_pk_bf16_f32 v17, v78, v79
	v_cvt_pk_bf16_f32 v16, v82, v83
	ds_write_b128 v34, v[16:19] offset:17408
	v_cvt_pk_bf16_f32 v19, v68, v69
	v_cvt_pk_bf16_f32 v18, v72, v73
	v_cvt_pk_bf16_f32 v17, v76, v77
	v_cvt_pk_bf16_f32 v16, v80, v81
	ds_write_b128 v34, v[16:19] offset:17424
	v_cvt_pk_bf16_f32 v19, v92, v93
	v_cvt_pk_bf16_f32 v18, v94, v95
	v_cvt_pk_bf16_f32 v17, v96, v97
	v_cvt_pk_bf16_f32 v16, v66, v67
	ds_write_b128 v34, v[16:19]
	v_cvt_pk_bf16_f32 v19, v84, v85
	v_cvt_pk_bf16_f32 v18, v86, v87
	v_cvt_pk_bf16_f32 v17, v88, v89
	v_cvt_pk_bf16_f32 v16, v90, v91
	v_lshl_add_u32 v35, v63, 2, s94
	ds_write_b128 v34, v[16:19] offset:16
	s_waitcnt lgkmcnt(0)
	s_barrier
	ds_read2st64_b32 v[20:21], v35 offset0:1 offset1:2
	v_lshlrev_b32_e32 v16, 10, v63
	v_add3_u32 v23, s88, v16, v60
	v_ashrrev_i32_e32 v38, 6, v64
	v_and_b32_e32 v39, 15, v64
	s_waitcnt lgkmcnt(0)
	v_pk_mul_f32 v[0:1], v[0:1], v[20:21] op_sel_hi:[1,0]
	v_pk_mul_f32 v[2:3], v[2:3], v[20:21] op_sel_hi:[1,0]
	v_mov_b32_e32 v22, v21
	ds_write_b128 v23, v[0:3]
	v_pk_mul_f32 v[0:1], v[96:97], v[20:21] op_sel_hi:[1,0]
	v_pk_mul_f32 v[2:3], v[94:95], v[20:21] op_sel_hi:[1,0]
	v_pk_mul_f32 v[18:19], v[22:23], v[0:1] op_sel_hi:[0,1]
	v_pk_mul_f32 v[0:1], v[4:5], v[20:21] op_sel_hi:[1,0]
	v_pk_mul_f32 v[4:5], v[22:23], v[2:3] op_sel_hi:[0,1]
	v_pk_mul_f32 v[2:3], v[6:7], v[20:21] op_sel_hi:[1,0]
	ds_write_b128 v23, v[0:3] offset:16
	v_pk_mul_f32 v[0:1], v[92:93], v[20:21] op_sel_hi:[1,0]
	v_pk_mul_f32 v[2:3], v[90:91], v[20:21] op_sel_hi:[1,0]
	v_pk_mul_f32 v[6:7], v[22:23], v[0:1] op_sel_hi:[0,1]
	ds_write_b128 v23, v[4:7] offset:528
	v_pk_mul_f32 v[0:1], v[8:9], v[20:21] op_sel_hi:[1,0]
	v_pk_mul_f32 v[4:5], v[22:23], v[2:3] op_sel_hi:[0,1]
	v_pk_mul_f32 v[2:3], v[12:13], v[20:21] op_sel_hi:[1,0]
	ds_write_b128 v23, v[0:3] offset:32
	v_pk_mul_f32 v[0:1], v[88:89], v[20:21] op_sel_hi:[1,0]
	v_pk_mul_f32 v[2:3], v[86:87], v[20:21] op_sel_hi:[1,0]
	v_pk_mul_f32 v[6:7], v[22:23], v[0:1] op_sel_hi:[0,1]
	ds_write_b128 v23, v[4:7] offset:544
	v_pk_mul_f32 v[0:1], v[14:15], v[20:21] op_sel_hi:[1,0]
	v_pk_mul_f32 v[4:5], v[22:23], v[2:3] op_sel_hi:[0,1]
	v_pk_mul_f32 v[2:3], v[10:11], v[20:21] op_sel_hi:[1,0]
	v_pk_mul_f32 v[16:17], v[66:67], v[20:21] op_sel_hi:[1,0]
	ds_write_b128 v23, v[0:3] offset:48
	v_pk_mul_f32 v[0:1], v[84:85], v[20:21] op_sel_hi:[1,0]
	v_pk_mul_f32 v[16:17], v[22:23], v[16:17] op_sel_hi:[0,1]
	v_pk_mul_f32 v[6:7], v[22:23], v[0:1] op_sel_hi:[0,1]
	v_lshlrev_b32_e32 v1, 4, v38
	ds_write_b128 v23, v[16:19] offset:512
	v_and_b32_e32 v16, 48, v1
	v_cmp_gt_i32_e64 s[2:3], 4, v38
	v_mov_b32_e32 v0, s97
	v_or_b32_e32 v1, v16, v39
	v_cndmask_b32_e64 v0, v0, 0, s[2:3]
	v_mul_u32_u24_e32 v1, 0x110, v1
	v_and_b32_e32 v2, 48, v163
	ds_write_b128 v23, v[4:7] offset:560
	v_add3_u32 v17, v0, v1, v2
	v_add_u32_e32 v19, 0, v2
	ds_read_b128 v[0:3], v17
	v_mad_u32_u24 v18, v39, s57, v19
	ds_read_b128 v[4:7], v18
	ds_read_b128 v[8:11], v18 offset:4352
	ds_read_b128 v[12:15], v18 offset:8704
	ds_read_b128 v[20:23], v18 offset:13056
	s_waitcnt lgkmcnt(3)
	v_mfma_f32_16x16x32_bf16 v[4:7], v[0:3], v[4:7], 0
	v_lshrrev_b32_e32 v27, 4, v163
	v_lshl_or_b32 v16, v27, 2, v16
	v_cmp_lt_i32_e32 vcc, 3, v38
	s_waitcnt lgkmcnt(2)
	v_mfma_f32_16x16x32_bf16 v[8:11], v[0:3], v[8:11], 0
	s_waitcnt lgkmcnt(1)
	v_mfma_f32_16x16x32_bf16 v[12:15], v[0:3], v[12:15], 0
	s_waitcnt lgkmcnt(0)
	v_mfma_f32_16x16x32_bf16 v[0:3], v[0:3], v[20:23], 0
	ds_read_b128 v[20:23], v17 offset:64
	ds_read_b128 v[28:31], v18 offset:64
	s_waitcnt lgkmcnt(0)
	v_mfma_f32_16x16x32_bf16 v[4:7], v[20:23], v[28:31], v[4:7]
	ds_read_b128 v[28:31], v18 offset:4416
	s_waitcnt lgkmcnt(0)
	v_mfma_f32_16x16x32_bf16 v[8:11], v[20:23], v[28:31], v[8:11]
	ds_read_b128 v[28:31], v18 offset:8768
	s_waitcnt lgkmcnt(0)
	v_mfma_f32_16x16x32_bf16 v[12:15], v[20:23], v[28:31], v[12:15]
	ds_read_b128 v[28:31], v18 offset:13120
	s_waitcnt lgkmcnt(0)
	v_mfma_f32_16x16x32_bf16 v[0:3], v[20:23], v[28:31], v[0:3]
	ds_read_b128 v[20:23], v17 offset:128
	ds_read_b128 v[28:31], v18 offset:128
	s_waitcnt lgkmcnt(0)
	v_mfma_f32_16x16x32_bf16 v[4:7], v[20:23], v[28:31], v[4:7]
	ds_read_b128 v[28:31], v18 offset:4480
	s_waitcnt lgkmcnt(0)
	v_mfma_f32_16x16x32_bf16 v[8:11], v[20:23], v[28:31], v[8:11]
	ds_read_b128 v[28:31], v18 offset:8832
	s_waitcnt lgkmcnt(0)
	v_mfma_f32_16x16x32_bf16 v[28:31], v[20:23], v[28:31], v[12:15]
	s_nop 2
	ds_read_b128 v[12:15], v18 offset:13184
	s_waitcnt lgkmcnt(0)
	v_mfma_f32_16x16x32_bf16 v[0:3], v[20:23], v[12:15], v[0:3]
	ds_read_b128 v[20:23], v17 offset:192
	ds_read_b128 v[12:15], v18 offset:192
	v_lshl_add_u32 v17, v39, 1, 0
	s_waitcnt lgkmcnt(0)
	v_mfma_f32_16x16x32_bf16 v[12:15], v[20:23], v[12:15], v[4:7]
	s_nop 2
	ds_read_b128 v[4:7], v18 offset:4544
	s_waitcnt lgkmcnt(0)
	v_mfma_f32_16x16x32_bf16 v[8:11], v[20:23], v[4:7], v[8:11]
	ds_read_b128 v[4:7], v18 offset:8896
	s_waitcnt lgkmcnt(0)
	v_mfma_f32_16x16x32_bf16 v[4:7], v[20:23], v[4:7], v[28:31]
	s_nop 2
	ds_read_b128 v[28:31], v18 offset:13248
	v_lshl_add_u32 v18, v39, 2, s94
	s_waitcnt lgkmcnt(0)
	v_mfma_f32_16x16x32_bf16 v[0:3], v[20:23], v[28:31], v[0:3]
	v_and_b32_e32 v184, 15, v224
	v_bfe_u32 v185, v224, 4, 2
	v_lshrrev_b32_e32 v186, 6, v224
	v_and_b32_e32 v187, 3, v186
	v_lshlrev_b32_e32 v188, 2, v185
	v_lshl_add_u32 v188, v187, 4, v188
	v_lshlrev_b32_e32 v189, 2, v188
	v_add_u32_e32 v189, 0x27c00, v189
	v_lshlrev_b32_e32 v190, 2, v184
	v_add_u32_e32 v190, 0x27c00, v190
	ds_read_b128 v[192:195], v189
	ds_read_b128 v[196:199], v189 offset:256
	ds_read_b32 v200, v190
	ds_read_b32 v201, v190 offset:64
	ds_read_b32 v202, v190 offset:128
	ds_read_b32 v203, v190 offset:192
	v_add_u32_e32 v204, 0, v188
	v_add_u32_e32 v205, 1, v188
	v_add_u32_e32 v206, 2, v188
	v_add_u32_e32 v207, 3, v188
	v_add_u32_e32 v208, 0, v184
	v_add_u32_e32 v209, 16, v184
	v_add_u32_e32 v210, 32, v184
	v_add_u32_e32 v211, 48, v184
	v_readfirstlane_b32 s98, v186
	s_nop 7
	s_nop 7
	s_waitcnt lgkmcnt(0)
	s_cmp_lt_u32 s98, 4
	s_cbranch_scc0 .Lkk2_qk
; __device__ __forceinline__ float delta_prep(const Params& p, int l, int h, bool isP, int grow0, int t0, int nvalid, int bb, char* sm) {
;     ...
;     float* Mm = (float*)(sm + L_MM);
;     bfraw* qk = (bfraw*)(sm + L_QK);
; #pragma unroll
;     for (int nt = 0; nt < 4; ++nt)
; #pragma unroll
;       for (int g = 0; g < 4; ++g) {
;         const int i = mt * 16 + q * 4 + g, j = nt * 16 + r;
;         const float Gi = misc[i], Gj = misc[j];
;         if (w < 4) {
;           float v = (j < i) ? acc[nt][g] * __expf(Gi - Gj) * misc[64 + i] : 0.f;
;           Mm[j * 64 + i] = v;
;           ((bfraw*)(sm + L_KGT))[i * 72 + j] = f2bf(v);
	v_lshlrev_b32_e32 v212, 8, v184
	v_lshl_add_u32 v212, v188, 2, v212
	v_add_u32_e32 v212, 0x23c00, v212
	v_mul_u32_u24_e32 v213, 0x90, v188
	v_lshl_add_u32 v213, v184, 1, v213
	v_sub_f32_e32 v214, v192, v200
	v_mul_f32_e32 v214, 0x3fb8aa3b, v214
	v_exp_f32_e32 v215, v214
	v_cmp_lt_u32_e32 vcc, v208, v204
	v_mul_f32_e32 v216, v12, v215
	v_mul_f32_e32 v216, v216, v196
	v_cndmask_b32_e32 v220, 0, v216, vcc
	v_sub_f32_e32 v214, v193, v200
	v_mul_f32_e32 v214, 0x3fb8aa3b, v214
	v_exp_f32_e32 v215, v214
	v_cmp_lt_u32_e32 vcc, v208, v205
	v_mul_f32_e32 v216, v13, v215
	v_mul_f32_e32 v216, v216, v197
	v_cndmask_b32_e32 v221, 0, v216, vcc
	v_sub_f32_e32 v214, v194, v200
	v_mul_f32_e32 v214, 0x3fb8aa3b, v214
	v_exp_f32_e32 v215, v214
	v_cmp_lt_u32_e32 vcc, v208, v206
	v_mul_f32_e32 v216, v14, v215
	v_mul_f32_e32 v216, v216, v198
	v_cndmask_b32_e32 v222, 0, v216, vcc
	v_sub_f32_e32 v214, v195, v200
	v_mul_f32_e32 v214, 0x3fb8aa3b, v214
	v_exp_f32_e32 v215, v214
	v_cmp_lt_u32_e32 vcc, v208, v207
	v_mul_f32_e32 v216, v15, v215
	v_mul_f32_e32 v216, v216, v199
	v_cndmask_b32_e32 v223, 0, v216, vcc
	ds_write_b128 v212, v[220:223] offset:0
	v_cvt_pk_bf16_f32 v216, v220, v220
	ds_write_b16 v213, v216 offset:34816
	v_cvt_pk_bf16_f32 v216, v221, v221
	ds_write_b16 v213, v216 offset:34960
	v_cvt_pk_bf16_f32 v216, v222, v222
	ds_write_b16 v213, v216 offset:35104
	v_cvt_pk_bf16_f32 v216, v223, v223
	ds_write_b16 v213, v216 offset:35248
	v_sub_f32_e32 v214, v192, v201
	v_mul_f32_e32 v214, 0x3fb8aa3b, v214
	v_exp_f32_e32 v215, v214
	v_cmp_lt_u32_e32 vcc, v209, v204
	v_mul_f32_e32 v216, v8, v215
	v_mul_f32_e32 v216, v216, v196
	v_cndmask_b32_e32 v220, 0, v216, vcc
	v_sub_f32_e32 v214, v193, v201
	v_mul_f32_e32 v214, 0x3fb8aa3b, v214
	v_exp_f32_e32 v215, v214
	v_cmp_lt_u32_e32 vcc, v209, v205
	v_mul_f32_e32 v216, v9, v215
	v_mul_f32_e32 v216, v216, v197
	v_cndmask_b32_e32 v221, 0, v216, vcc
	v_sub_f32_e32 v214, v194, v201
	v_mul_f32_e32 v214, 0x3fb8aa3b, v214
	v_exp_f32_e32 v215, v214
	v_cmp_lt_u32_e32 vcc, v209, v206
	v_mul_f32_e32 v216, v10, v215
	v_mul_f32_e32 v216, v216, v198
	v_cndmask_b32_e32 v222, 0, v216, vcc
	v_sub_f32_e32 v214, v195, v201
	v_mul_f32_e32 v214, 0x3fb8aa3b, v214
	v_exp_f32_e32 v215, v214
	v_cmp_lt_u32_e32 vcc, v209, v207
	v_mul_f32_e32 v216, v11, v215
	v_mul_f32_e32 v216, v216, v199
	v_cndmask_b32_e32 v223, 0, v216, vcc
	ds_write_b128 v212, v[220:223] offset:4096
	v_cvt_pk_bf16_f32 v216, v220, v220
	ds_write_b16 v213, v216 offset:34848
	v_cvt_pk_bf16_f32 v216, v221, v221
	ds_write_b16 v213, v216 offset:34992
	v_cvt_pk_bf16_f32 v216, v222, v222
	ds_write_b16 v213, v216 offset:35136
	v_cvt_pk_bf16_f32 v216, v223, v223
	ds_write_b16 v213, v216 offset:35280
	v_sub_f32_e32 v214, v192, v202
	v_mul_f32_e32 v214, 0x3fb8aa3b, v214
	v_exp_f32_e32 v215, v214
	v_cmp_lt_u32_e32 vcc, v210, v204
	v_mul_f32_e32 v216, v4, v215
	v_mul_f32_e32 v216, v216, v196
	v_cndmask_b32_e32 v220, 0, v216, vcc
	v_sub_f32_e32 v214, v193, v202
	v_mul_f32_e32 v214, 0x3fb8aa3b, v214
	v_exp_f32_e32 v215, v214
	v_cmp_lt_u32_e32 vcc, v210, v205
	v_mul_f32_e32 v216, v5, v215
	v_mul_f32_e32 v216, v216, v197
	v_cndmask_b32_e32 v221, 0, v216, vcc
	v_sub_f32_e32 v214, v194, v202
	v_mul_f32_e32 v214, 0x3fb8aa3b, v214
	v_exp_f32_e32 v215, v214
	v_cmp_lt_u32_e32 vcc, v210, v206
	v_mul_f32_e32 v216, v6, v215
	v_mul_f32_e32 v216, v216, v198
	v_cndmask_b32_e32 v222, 0, v216, vcc
	v_sub_f32_e32 v214, v195, v202
	v_mul_f32_e32 v214, 0x3fb8aa3b, v214
	v_exp_f32_e32 v215, v214
	v_cmp_lt_u32_e32 vcc, v210, v207
	v_mul_f32_e32 v216, v7, v215
	v_mul_f32_e32 v216, v216, v199
	v_cndmask_b32_e32 v223, 0, v216, vcc
	ds_write_b128 v212, v[220:223] offset:8192
	v_cvt_pk_bf16_f32 v216, v220, v220
	ds_write_b16 v213, v216 offset:34880
	v_cvt_pk_bf16_f32 v216, v221, v221
	ds_write_b16 v213, v216 offset:35024
	v_cvt_pk_bf16_f32 v216, v222, v222
	ds_write_b16 v213, v216 offset:35168
	v_cvt_pk_bf16_f32 v216, v223, v223
	ds_write_b16 v213, v216 offset:35312
	v_sub_f32_e32 v214, v192, v203
	v_mul_f32_e32 v214, 0x3fb8aa3b, v214
	v_exp_f32_e32 v215, v214
	v_cmp_lt_u32_e32 vcc, v211, v204
	v_mul_f32_e32 v216, v0, v215
	v_mul_f32_e32 v216, v216, v196
	v_cndmask_b32_e32 v220, 0, v216, vcc
	v_sub_f32_e32 v214, v193, v203
	v_mul_f32_e32 v214, 0x3fb8aa3b, v214
	v_exp_f32_e32 v215, v214
	v_cmp_lt_u32_e32 vcc, v211, v205
	v_mul_f32_e32 v216, v1, v215
	v_mul_f32_e32 v216, v216, v197
	v_cndmask_b32_e32 v221, 0, v216, vcc
	v_sub_f32_e32 v214, v194, v203
	v_mul_f32_e32 v214, 0x3fb8aa3b, v214
	v_exp_f32_e32 v215, v214
	v_cmp_lt_u32_e32 vcc, v211, v206
	v_mul_f32_e32 v216, v2, v215
	v_mul_f32_e32 v216, v216, v198
	v_cndmask_b32_e32 v222, 0, v216, vcc
	v_sub_f32_e32 v214, v195, v203
	v_mul_f32_e32 v214, 0x3fb8aa3b, v214
	v_exp_f32_e32 v215, v214
	v_cmp_lt_u32_e32 vcc, v211, v207
	v_mul_f32_e32 v216, v3, v215
	v_mul_f32_e32 v216, v216, v199
	v_cndmask_b32_e32 v223, 0, v216, vcc
	ds_write_b128 v212, v[220:223] offset:12288
	v_cvt_pk_bf16_f32 v216, v220, v220
	ds_write_b16 v213, v216 offset:34912
	v_cvt_pk_bf16_f32 v216, v221, v221
	ds_write_b16 v213, v216 offset:35056
	v_cvt_pk_bf16_f32 v216, v222, v222
	ds_write_b16 v213, v216 offset:35200
	v_cvt_pk_bf16_f32 v216, v223, v223
	ds_write_b16 v213, v216 offset:35344
	s_branch .Lkk2_end

; __device__ __forceinline__ float delta_prep(const Params& p, int l, int h, bool isP, int grow0, int t0, int nvalid, int bb, char* sm) {
;     ...
;     bfraw* qh = (bfraw*)(sm + L_QG);
;     bfraw* kh = (bfraw*)(sm + L_W);
;     *(uint4*)(qh + rl * 136 + cg8 * 16) = pack8(qf); *(uint4*)(qh + rl * 136 + cg8 * 16 + 8) = pack8(qf + 8);
;     *(uint4*)(kh + rl * 136 + cg8 * 16) = pack8(kf); *(uint4*)(kh + rl * 136 + cg8 * 16 + 8) = pack8(kf + 8);
;   }
;   __syncthreads();
;   {
;     float* rhs = (float*)(sm + L_RHS);
;     const float bt = misc[64 + rl], eg = misc[128 + rl];
; #pragma unroll
;     for (int e = 0; e < 16; ++e) {
;       rhs[rl * 256 + cg8 * 16 + e] = vf[e] * bt;
;       rhs[rl * 256 + 128 + cg8 * 16 + e] = kf[e] * bt * eg;
;     }
;   }
;   {
;     const bfraw* kh = (const bfraw*)(sm + L_W);
;     const bfraw* ah = (w < 4) ? kh : (const bfraw*)(sm + L_QG);
;     const int mt = w & 3;
;     f32x4 acc[4];
; #pragma unroll
;     for (int i = 0; i < 4; ++i) acc[i] = (f32x4){0.f, 0.f, 0.f, 0.f};
; #pragma unroll
;     for (int kk = 0; kk < 4; ++kk) {
;       bf16x8 af = *(const bf16x8*)(ah + (mt * 16 + r) * 136 + kk * 32 + q * 8);
; #pragma unroll
;       for (int nt = 0; nt < 4; ++nt) {
;         bf16x8 bfr = *(const bf16x8*)(kh + (nt * 16 + r) * 136 + kk * 32 + q * 8);
;         acc[nt] = mfma16(af, bfr, acc[nt]);
;       }
;     }
;     float* Mm = (float*)(sm + L_MM);
;     bfraw* qk = (bfraw*)(sm + L_QK);
; #pragma unroll
;     for (int nt = 0; nt < 4; ++nt)
; #pragma unroll
;       for (int g = 0; g < 4; ++g) {
;         const int i = mt * 16 + q * 4 + g, j = nt * 16 + r;
;         const float Gi = misc[i], Gj = misc[j];
.LBB0_4108:
	s_or_b64 exec, exec, s[0:1]
	v_mul_lo_u32 v20, v3, s50
	v_lshlrev_b32_e32 v21, 1, v65
	v_add3_u32 v38, 0, v20, v21
	v_cvt_pk_bf16_f32 v23, v70, v71
	v_cvt_pk_bf16_f32 v22, v74, v75
	v_cvt_pk_bf16_f32 v21, v78, v79
	v_cvt_pk_bf16_f32 v20, v82, v83
	ds_write_b128 v38, v[20:23] offset:17408
	v_cvt_pk_bf16_f32 v23, v68, v69
	v_cvt_pk_bf16_f32 v22, v72, v73
	v_cvt_pk_bf16_f32 v21, v76, v77
	v_cvt_pk_bf16_f32 v20, v80, v81
	ds_write_b128 v38, v[20:23] offset:17424
	v_cvt_pk_bf16_f32 v23, v92, v93
	v_cvt_pk_bf16_f32 v22, v94, v95
	v_cvt_pk_bf16_f32 v21, v96, v97
	v_cvt_pk_bf16_f32 v20, v66, v67
	ds_write_b128 v38, v[20:23]
	v_cvt_pk_bf16_f32 v23, v84, v85
	v_cvt_pk_bf16_f32 v22, v86, v87
	v_cvt_pk_bf16_f32 v21, v88, v89
	v_cvt_pk_bf16_f32 v20, v90, v91
	v_lshl_add_u32 v39, v3, 2, s92
	ds_write_b128 v38, v[20:23] offset:16
	s_waitcnt lgkmcnt(0)
	s_barrier
	ds_read2st64_b32 v[26:27], v39 offset0:1 offset1:2
	v_lshlrev_b32_e32 v22, 10, v3
	v_add3_u32 v29, s48, v22, v98
	v_ashrrev_i32_e32 v21, 6, v0
	v_and_b32_e32 v20, 15, v0
	s_waitcnt lgkmcnt(0)
	v_pk_mul_f32 v[4:5], v[4:5], v[26:27] op_sel_hi:[1,0]
	v_pk_mul_f32 v[6:7], v[6:7], v[26:27] op_sel_hi:[1,0]
	v_mov_b32_e32 v28, v27
	ds_write_b128 v29, v[4:7]
	v_pk_mul_f32 v[4:5], v[96:97], v[26:27] op_sel_hi:[1,0]
	v_pk_mul_f32 v[6:7], v[94:95], v[26:27] op_sel_hi:[1,0]
	v_pk_mul_f32 v[24:25], v[28:29], v[4:5] op_sel_hi:[0,1]
	v_pk_mul_f32 v[4:5], v[8:9], v[26:27] op_sel_hi:[1,0]
	v_pk_mul_f32 v[8:9], v[28:29], v[6:7] op_sel_hi:[0,1]
	v_pk_mul_f32 v[6:7], v[10:11], v[26:27] op_sel_hi:[1,0]
	ds_write_b128 v29, v[4:7] offset:16
	v_pk_mul_f32 v[4:5], v[92:93], v[26:27] op_sel_hi:[1,0]
	v_pk_mul_f32 v[6:7], v[90:91], v[26:27] op_sel_hi:[1,0]
	v_pk_mul_f32 v[10:11], v[28:29], v[4:5] op_sel_hi:[0,1]
	ds_write_b128 v29, v[8:11] offset:528
	v_pk_mul_f32 v[4:5], v[12:13], v[26:27] op_sel_hi:[1,0]
	v_pk_mul_f32 v[8:9], v[28:29], v[6:7] op_sel_hi:[0,1]
	v_pk_mul_f32 v[6:7], v[16:17], v[26:27] op_sel_hi:[1,0]
	ds_write_b128 v29, v[4:7] offset:32
	v_pk_mul_f32 v[4:5], v[88:89], v[26:27] op_sel_hi:[1,0]
	v_pk_mul_f32 v[6:7], v[86:87], v[26:27] op_sel_hi:[1,0]
	v_pk_mul_f32 v[10:11], v[28:29], v[4:5] op_sel_hi:[0,1]
	ds_write_b128 v29, v[8:11] offset:544
	v_pk_mul_f32 v[4:5], v[18:19], v[26:27] op_sel_hi:[1,0]
	v_pk_mul_f32 v[8:9], v[28:29], v[6:7] op_sel_hi:[0,1]
	v_pk_mul_f32 v[6:7], v[14:15], v[26:27] op_sel_hi:[1,0]
	ds_write_b128 v29, v[4:7] offset:48
	v_pk_mul_f32 v[4:5], v[84:85], v[26:27] op_sel_hi:[1,0]
	v_lshlrev_b32_e32 v34, 4, v21
	v_pk_mul_f32 v[22:23], v[66:67], v[26:27] op_sel_hi:[1,0]
	v_pk_mul_f32 v[10:11], v[28:29], v[4:5] op_sel_hi:[0,1]
	v_cmp_gt_i32_e32 vcc, 4, v21
	v_mov_b32_e32 v4, s93
	v_and_or_b32 v5, v34, 48, v20
	v_pk_mul_f32 v[22:23], v[28:29], v[22:23] op_sel_hi:[0,1]
	ds_write_b128 v29, v[8:11] offset:560
	v_cndmask_b32_e64 v4, v4, 0, vcc
	v_mul_u32_u24_e32 v5, 0x110, v5
	v_and_b32_e32 v8, 48, v165
	ds_write_b128 v29, v[22:25] offset:512
	v_add3_u32 v35, v4, v5, v8
	ds_read_b128 v[4:7], v35
	v_mul_u32_u24_e32 v9, 0x110, v20
	v_add3_u32 v36, 0, v8, v9
	ds_read_b128 v[8:11], v36
	ds_read_b128 v[12:15], v36 offset:4352
	ds_read_b128 v[16:19], v36 offset:8704
	ds_read_b128 v[22:25], v36 offset:13056
	ds_read_b128 v[26:29], v35 offset:64
	s_waitcnt lgkmcnt(4)
	v_mfma_f32_16x16x32_bf16 v[8:11], v[4:7], v[8:11], 0
	v_cmp_lt_i32_e32 vcc, 3, v21
	v_lshrrev_b32_e32 v21, 2, v165
	v_bitop3_b32 v21, v34, 60, v21 bitop3:0xc8
	s_waitcnt lgkmcnt(3)
	v_mfma_f32_16x16x32_bf16 v[12:15], v[4:7], v[12:15], 0
	s_waitcnt lgkmcnt(2)
	v_mfma_f32_16x16x32_bf16 v[16:19], v[4:7], v[16:19], 0
	s_waitcnt lgkmcnt(1)
	v_mfma_f32_16x16x32_bf16 v[4:7], v[4:7], v[22:25], 0
	ds_read_b128 v[22:25], v36 offset:64
	s_waitcnt lgkmcnt(0)
	v_mfma_f32_16x16x32_bf16 v[8:11], v[26:29], v[22:25], v[8:11]
	ds_read_b128 v[22:25], v36 offset:4416
	s_waitcnt lgkmcnt(0)
	v_mfma_f32_16x16x32_bf16 v[12:15], v[26:29], v[22:25], v[12:15]
	ds_read_b128 v[22:25], v36 offset:8768
	ds_read_b128 v[30:33], v36 offset:13120
	s_waitcnt lgkmcnt(1)
	v_mfma_f32_16x16x32_bf16 v[16:19], v[26:29], v[22:25], v[16:19]
	ds_read_b128 v[22:25], v35 offset:128
	s_waitcnt lgkmcnt(1)
	v_mfma_f32_16x16x32_bf16 v[4:7], v[26:29], v[30:33], v[4:7]
	ds_read_b128 v[26:29], v36 offset:128
	s_waitcnt lgkmcnt(0)
	v_mfma_f32_16x16x32_bf16 v[8:11], v[22:25], v[26:29], v[8:11]
	ds_read_b128 v[26:29], v36 offset:4480
	s_waitcnt lgkmcnt(0)
	v_mfma_f32_16x16x32_bf16 v[12:15], v[22:25], v[26:29], v[12:15]
	ds_read_b128 v[26:29], v36 offset:8832
	ds_read_b128 v[30:33], v36 offset:13184
	ds_read_b128 v[40:43], v35 offset:192
	s_waitcnt lgkmcnt(2)
	v_mfma_f32_16x16x32_bf16 v[26:29], v[22:25], v[26:29], v[16:19]
	s_nop 2
	ds_read_b128 v[16:19], v36 offset:192
	s_waitcnt lgkmcnt(2)
	v_mfma_f32_16x16x32_bf16 v[4:7], v[22:25], v[30:33], v[4:7]
	ds_read_b128 v[22:25], v36 offset:13248
	s_waitcnt lgkmcnt(1)
	v_mfma_f32_16x16x32_bf16 v[16:19], v[40:43], v[16:19], v[8:11]
	s_nop 2
	ds_read_b128 v[8:11], v36 offset:4544
	s_waitcnt lgkmcnt(0)
	v_mfma_f32_16x16x32_bf16 v[12:15], v[40:43], v[8:11], v[12:15]
	ds_read_b128 v[8:11], v36 offset:8896
	s_waitcnt lgkmcnt(0)
	v_mfma_f32_16x16x32_bf16 v[8:11], v[40:43], v[8:11], v[26:29]
	s_nop 2
	v_lshl_add_u32 v27, v21, 2, s92
	v_lshl_add_u32 v26, v20, 2, s92
	ds_read_b32 v30, v27
	ds_read_b32 v37, v26
	v_mfma_f32_16x16x32_bf16 v[4:7], v[40:43], v[22:25], v[4:7]
	v_and_b32_e32 v184, 15, v224
	v_bfe_u32 v185, v224, 4, 2
	v_lshrrev_b32_e32 v186, 6, v224
	v_and_b32_e32 v187, 3, v186
	v_lshlrev_b32_e32 v188, 2, v185
	v_lshl_add_u32 v188, v187, 4, v188
	v_lshlrev_b32_e32 v189, 2, v188
	v_add_u32_e32 v189, 0x27c00, v189
	v_lshlrev_b32_e32 v190, 2, v184
	v_add_u32_e32 v190, 0x27c00, v190
	ds_read_b128 v[192:195], v189
	ds_read_b128 v[196:199], v189 offset:256
	ds_read_b32 v200, v190
	ds_read_b32 v201, v190 offset:64
	ds_read_b32 v202, v190 offset:128
	ds_read_b32 v203, v190 offset:192
	v_add_u32_e32 v204, 0, v188
	v_add_u32_e32 v205, 1, v188
	v_add_u32_e32 v206, 2, v188
	v_add_u32_e32 v207, 3, v188
	v_add_u32_e32 v208, 0, v184
	v_add_u32_e32 v209, 16, v184
	v_add_u32_e32 v210, 32, v184
	v_add_u32_e32 v211, 48, v184
	v_readfirstlane_b32 s98, v186
	s_nop 7
	s_nop 7
	s_waitcnt lgkmcnt(0)
	s_cmp_lt_u32 s98, 4
	s_cbranch_scc0 .Lkk3_qk
; __device__ __forceinline__ float delta_prep(const Params& p, int l, int h, bool isP, int grow0, int t0, int nvalid, int bb, char* sm) {
;     ...
;     float* Mm = (float*)(sm + L_MM);
;     bfraw* qk = (bfraw*)(sm + L_QK);
; #pragma unroll
;     for (int nt = 0; nt < 4; ++nt)
; #pragma unroll
;       for (int g = 0; g < 4; ++g) {
;         const int i = mt * 16 + q * 4 + g, j = nt * 16 + r;
;         const float Gi = misc[i], Gj = misc[j];
;         if (w < 4) {
;           float v = (j < i) ? acc[nt][g] * __expf(Gi - Gj) * misc[64 + i] : 0.f;
;           Mm[j * 64 + i] = v;
;           ((bfraw*)(sm + L_KGT))[i * 72 + j] = f2bf(v);
	v_lshlrev_b32_e32 v212, 8, v184
	v_lshl_add_u32 v212, v188, 2, v212
	v_add_u32_e32 v212, 0x23c00, v212
	v_mul_u32_u24_e32 v213, 0x90, v188
	v_lshl_add_u32 v213, v184, 1, v213
	v_sub_f32_e32 v214, v192, v200
	v_mul_f32_e32 v214, 0x3fb8aa3b, v214
	v_exp_f32_e32 v215, v214
	v_cmp_lt_u32_e32 vcc, v208, v204
	v_mul_f32_e32 v216, v16, v215
	v_mul_f32_e32 v216, v216, v196
	v_cndmask_b32_e32 v220, 0, v216, vcc
	v_sub_f32_e32 v214, v193, v200
	v_mul_f32_e32 v214, 0x3fb8aa3b, v214
	v_exp_f32_e32 v215, v214
	v_cmp_lt_u32_e32 vcc, v208, v205
	v_mul_f32_e32 v216, v17, v215
	v_mul_f32_e32 v216, v216, v197
	v_cndmask_b32_e32 v221, 0, v216, vcc
	v_sub_f32_e32 v214, v194, v200
	v_mul_f32_e32 v214, 0x3fb8aa3b, v214
	v_exp_f32_e32 v215, v214
	v_cmp_lt_u32_e32 vcc, v208, v206
	v_mul_f32_e32 v216, v18, v215
	v_mul_f32_e32 v216, v216, v198
	v_cndmask_b32_e32 v222, 0, v216, vcc
	v_sub_f32_e32 v214, v195, v200
	v_mul_f32_e32 v214, 0x3fb8aa3b, v214
	v_exp_f32_e32 v215, v214
	v_cmp_lt_u32_e32 vcc, v208, v207
	v_mul_f32_e32 v216, v19, v215
	v_mul_f32_e32 v216, v216, v199
	v_cndmask_b32_e32 v223, 0, v216, vcc
	ds_write_b128 v212, v[220:223] offset:0
	v_cvt_pk_bf16_f32 v216, v220, v220
	ds_write_b16 v213, v216 offset:34816
	v_cvt_pk_bf16_f32 v216, v221, v221
	ds_write_b16 v213, v216 offset:34960
	v_cvt_pk_bf16_f32 v216, v222, v222
	ds_write_b16 v213, v216 offset:35104
	v_cvt_pk_bf16_f32 v216, v223, v223
	ds_write_b16 v213, v216 offset:35248
	v_sub_f32_e32 v214, v192, v201
	v_mul_f32_e32 v214, 0x3fb8aa3b, v214
	v_exp_f32_e32 v215, v214
	v_cmp_lt_u32_e32 vcc, v209, v204
	v_mul_f32_e32 v216, v12, v215
	v_mul_f32_e32 v216, v216, v196
	v_cndmask_b32_e32 v220, 0, v216, vcc
	v_sub_f32_e32 v214, v193, v201
	v_mul_f32_e32 v214, 0x3fb8aa3b, v214
	v_exp_f32_e32 v215, v214
	v_cmp_lt_u32_e32 vcc, v209, v205
	v_mul_f32_e32 v216, v13, v215
	v_mul_f32_e32 v216, v216, v197
	v_cndmask_b32_e32 v221, 0, v216, vcc
	v_sub_f32_e32 v214, v194, v201
	v_mul_f32_e32 v214, 0x3fb8aa3b, v214
	v_exp_f32_e32 v215, v214
	v_cmp_lt_u32_e32 vcc, v209, v206
	v_mul_f32_e32 v216, v14, v215
	v_mul_f32_e32 v216, v216, v198
	v_cndmask_b32_e32 v222, 0, v216, vcc
	v_sub_f32_e32 v214, v195, v201
	v_mul_f32_e32 v214, 0x3fb8aa3b, v214
	v_exp_f32_e32 v215, v214
	v_cmp_lt_u32_e32 vcc, v209, v207
	v_mul_f32_e32 v216, v15, v215
	v_mul_f32_e32 v216, v216, v199
	v_cndmask_b32_e32 v223, 0, v216, vcc
	ds_write_b128 v212, v[220:223] offset:4096
	v_cvt_pk_bf16_f32 v216, v220, v220
	ds_write_b16 v213, v216 offset:34848
	v_cvt_pk_bf16_f32 v216, v221, v221
	ds_write_b16 v213, v216 offset:34992
	v_cvt_pk_bf16_f32 v216, v222, v222
	ds_write_b16 v213, v216 offset:35136
	v_cvt_pk_bf16_f32 v216, v223, v223
	ds_write_b16 v213, v216 offset:35280
	v_sub_f32_e32 v214, v192, v202
	v_mul_f32_e32 v214, 0x3fb8aa3b, v214
	v_exp_f32_e32 v215, v214
	v_cmp_lt_u32_e32 vcc, v210, v204
	v_mul_f32_e32 v216, v8, v215
	v_mul_f32_e32 v216, v216, v196
	v_cndmask_b32_e32 v220, 0, v216, vcc
	v_sub_f32_e32 v214, v193, v202
	v_mul_f32_e32 v214, 0x3fb8aa3b, v214
	v_exp_f32_e32 v215, v214
	v_cmp_lt_u32_e32 vcc, v210, v205
	v_mul_f32_e32 v216, v9, v215
	v_mul_f32_e32 v216, v216, v197
	v_cndmask_b32_e32 v221, 0, v216, vcc
	v_sub_f32_e32 v214, v194, v202
	v_mul_f32_e32 v214, 0x3fb8aa3b, v214
	v_exp_f32_e32 v215, v214
	v_cmp_lt_u32_e32 vcc, v210, v206
	v_mul_f32_e32 v216, v10, v215
	v_mul_f32_e32 v216, v216, v198
	v_cndmask_b32_e32 v222, 0, v216, vcc
	v_sub_f32_e32 v214, v195, v202
	v_mul_f32_e32 v214, 0x3fb8aa3b, v214
	v_exp_f32_e32 v215, v214
	v_cmp_lt_u32_e32 vcc, v210, v207
	v_mul_f32_e32 v216, v11, v215
	v_mul_f32_e32 v216, v216, v199
	v_cndmask_b32_e32 v223, 0, v216, vcc
	ds_write_b128 v212, v[220:223] offset:8192
	v_cvt_pk_bf16_f32 v216, v220, v220
	ds_write_b16 v213, v216 offset:34880
	v_cvt_pk_bf16_f32 v216, v221, v221
	ds_write_b16 v213, v216 offset:35024
	v_cvt_pk_bf16_f32 v216, v222, v222
	ds_write_b16 v213, v216 offset:35168
	v_cvt_pk_bf16_f32 v216, v223, v223
	ds_write_b16 v213, v216 offset:35312
	v_sub_f32_e32 v214, v192, v203
	v_mul_f32_e32 v214, 0x3fb8aa3b, v214
	v_exp_f32_e32 v215, v214
	v_cmp_lt_u32_e32 vcc, v211, v204
	v_mul_f32_e32 v216, v4, v215
	v_mul_f32_e32 v216, v216, v196
	v_cndmask_b32_e32 v220, 0, v216, vcc
	v_sub_f32_e32 v214, v193, v203
	v_mul_f32_e32 v214, 0x3fb8aa3b, v214
	v_exp_f32_e32 v215, v214
	v_cmp_lt_u32_e32 vcc, v211, v205
	v_mul_f32_e32 v216, v5, v215
	v_mul_f32_e32 v216, v216, v197
	v_cndmask_b32_e32 v221, 0, v216, vcc
	v_sub_f32_e32 v214, v194, v203
	v_mul_f32_e32 v214, 0x3fb8aa3b, v214
	v_exp_f32_e32 v215, v214
	v_cmp_lt_u32_e32 vcc, v211, v206
	v_mul_f32_e32 v216, v6, v215
	v_mul_f32_e32 v216, v216, v198
	v_cndmask_b32_e32 v222, 0, v216, vcc
	v_sub_f32_e32 v214, v195, v203
	v_mul_f32_e32 v214, 0x3fb8aa3b, v214
	v_exp_f32_e32 v215, v214
	v_cmp_lt_u32_e32 vcc, v211, v207
	v_mul_f32_e32 v216, v7, v215
	v_mul_f32_e32 v216, v216, v199
	v_cndmask_b32_e32 v223, 0, v216, vcc
	ds_write_b128 v212, v[220:223] offset:12288
	v_cvt_pk_bf16_f32 v216, v220, v220
	ds_write_b16 v213, v216 offset:34912
	v_cvt_pk_bf16_f32 v216, v221, v221
	ds_write_b16 v213, v216 offset:35056
	v_cvt_pk_bf16_f32 v216, v222, v222
	ds_write_b16 v213, v216 offset:35200
	v_cvt_pk_bf16_f32 v216, v223, v223
	ds_write_b16 v213, v216 offset:35344
	s_branch .Lkk3_end
